# removed the 24 duplicated s_waitcnt lgkmcnt(0) (same wait twice in a row) in the four GEMM K-loops
# speedup vs baseline: 1.0419x; 1.0050x over previous
; #define PG8_STAGE(bufoff, gbase, voff) do { _Pragma("unroll") for (int _i = 0; _i < 2; ++_i) \
;         __builtin_amdgcn_global_load_lds((const unsigned*)((const char*)(gbase) + (voff)[_i]), (PG8_LAS unsigned*)(lds + (bufoff) + ldsw + _i * 8192), 16, 0, 0); } while (0)
; #define PG8_LDA(dst, b, h) do { _Pragma("unroll") for (int m = 0; m < 4; ++m) _Pragma("unroll") for (int k = 0; k < 2; ++k) dst[m][k] = *(const PG8_LAS bf16x8*)(lds + PG8_SA(b, h) + aoff + m * 2048 + k * 1024); } while (0)
; #define PG8_LDB(dst, b, h) do { _Pragma("unroll") for (int n = 0; n < 2; ++n) _Pragma("unroll") for (int k = 0; k < 2; ++k) dst[n][k] = *(const PG8_LAS bf16x8*)(lds + PG8_SB(b, h) + boff + n * 2048 + k * 1024); } while (0)
; #define PG8_MMA(ai, bj, At, Bt) do { __builtin_amdgcn_s_setprio(1); _Pragma("unroll") for (int m = 0; m < 4; ++m) _Pragma("unroll") for (int n = 0; n < 2; ++n) _Pragma("unroll") for (int k = 0; k < 2; ++k) \
;         acc[ai][bj][m][n] = __builtin_amdgcn_mfma_f32_16x16x32_bf16(Bt[n][k], At[m][k], acc[ai][bj][m][n], 0, 0, 0); __builtin_amdgcn_s_setprio(0); } while (0)
; #define PG8_WAIT_L(n) asm volatile("s_waitcnt lgkmcnt(" #n ")" ::: "memory")
; #define PG8_BAR __builtin_amdgcn_s_barrier()
; #define PG8_SCHED __builtin_amdgcn_sched_barrier(0)
; template <class Epi, class Sched>
; __device__ __forceinline__ void gemm_phase(PG8_LAS unsigned char* lds, const Gemm g, const Sched& S, const Epi& E) {
;     ...
;             PG8_LDB(B0, 0, 0); PG8_SCHED; PG8_LDA(At, 0, 0); PG8_STAGE(PG8_SA(1, 1), a1 + hstep, voffA);
;             PG8_WAIT_L(8); PG8_BAR; PG8_WAIT_L(0); PG8_MMA(0, 0, At, B0); PG8_BAR; PG8_SCHED;
;             PG8_LDB(B1, 0, 1); PG8_STAGE(PG8_SB(0, 0), b2, voffB);
;             PG8_BAR; PG8_WAIT_L(0); PG8_MMA(0, 1, At, B1); PG8_BAR;
;             PG8_LDA(At, 0, 1); PG8_STAGE(PG8_SA(0, 0), a2, voffA);
;             PG8_BAR; PG8_WAIT_L(0); PG8_MMA(1, 0, At, B0); PG8_BAR; PG8_SCHED;
.LBB0_96:
	s_add_u32 s10, s8, 0x100
	s_addc_u32 s11, s9, 0
	s_add_i32 s46, 0, 0x10000
	v_add_u32_e32 v154, s46, v139
	ds_read_b128 v[142:145], v154
	ds_read_b128 v[146:149], v154 offset:1024
	ds_read_b128 v[150:153], v154 offset:2048
	ds_read_b128 v[154:157], v154 offset:3072
	s_cmp_eq_u32 s45, 40
	s_cselect_b32 s15, s1, s11
	s_cselect_b32 s14, s0, s10
	s_cselect_b32 s13, s5, s44
	s_cselect_b32 s12, s4, s43
	v_lshl_add_u64 v[174:175], s[8:9], 0, v[134:135]
	s_add_i32 m0, s20, 0xc000
	ds_read_b128 v[158:161], v141
	ds_read_b128 v[162:165], v141 offset:1024
	ds_read_b128 v[166:169], v141 offset:2048
	ds_read_b128 v[170:173], v141 offset:3072
	ds_read_b128 v[178:181], v141 offset:4096
	ds_read_b128 v[182:185], v141 offset:5120
	ds_read_b128 v[186:189], v141 offset:6144
	ds_read_b128 v[190:193], v141 offset:7168
	global_load_lds_dwordx4 v[174:175], off
	v_lshl_add_u64 v[174:175], s[8:9], 0, v[136:137]
	s_add_i32 m0, s20, 0xe000
	s_nop 0
	global_load_lds_dwordx4 v[174:175], off
	s_waitcnt lgkmcnt(8)
	s_barrier
	s_waitcnt lgkmcnt(0)
	s_setprio 1
	v_mfma_f32_16x16x32_bf16 v[124:127], v[142:145], v[158:161], v[124:127]
	v_mfma_f32_16x16x32_bf16 v[120:123], v[150:153], v[158:161], v[120:123]
	v_mfma_f32_16x16x32_bf16 v[116:119], v[142:145], v[166:169], v[116:119]
	v_mfma_f32_16x16x32_bf16 v[112:115], v[150:153], v[166:169], v[112:115]
	v_mfma_f32_16x16x32_bf16 v[100:103], v[142:145], v[178:181], v[100:103]
	v_mfma_f32_16x16x32_bf16 v[96:99], v[150:153], v[178:181], v[96:99]
	v_mfma_f32_16x16x32_bf16 v[84:87], v[142:145], v[186:189], v[84:87]
	v_mfma_f32_16x16x32_bf16 v[80:83], v[150:153], v[186:189], v[80:83]
	v_mfma_f32_16x16x32_bf16 v[124:127], v[146:149], v[162:165], v[124:127]
	v_mfma_f32_16x16x32_bf16 v[120:123], v[154:157], v[162:165], v[120:123]
	v_mfma_f32_16x16x32_bf16 v[116:119], v[146:149], v[170:173], v[116:119]
	v_mfma_f32_16x16x32_bf16 v[112:115], v[154:157], v[170:173], v[112:115]
	v_mfma_f32_16x16x32_bf16 v[100:103], v[146:149], v[182:185], v[100:103]
	v_mfma_f32_16x16x32_bf16 v[96:99], v[154:157], v[182:185], v[96:99]
	v_mfma_f32_16x16x32_bf16 v[84:87], v[146:149], v[190:193], v[84:87]
	v_mfma_f32_16x16x32_bf16 v[80:83], v[154:157], v[190:193], v[80:83]
	s_setprio 0
	s_barrier
	s_add_i32 s47, 0, 0x14000
	v_add_u32_e32 v174, s47, v139
	s_add_i32 s8, s46, s18
	ds_read_b128 v[194:197], v174
	ds_read_b128 v[198:201], v174 offset:1024
	ds_read_b128 v[202:205], v174 offset:2048
	ds_read_b128 v[206:209], v174 offset:3072
	v_lshl_add_u64 v[174:175], s[12:13], 0, v[176:177]
	s_mov_b32 m0, s8
	v_lshl_add_u64 v[210:211], s[12:13], 0, v[128:129]
	global_load_lds_dwordx4 v[174:175], off
	s_add_i32 m0, s8, 0x2000
	s_nop 0
	global_load_lds_dwordx4 v[210:211], off
	s_barrier
	s_waitcnt lgkmcnt(0)
	s_setprio 1
	v_mfma_f32_16x16x32_bf16 v[108:111], v[194:197], v[158:161], v[108:111]
	v_mfma_f32_16x16x32_bf16 v[104:107], v[202:205], v[158:161], v[104:107]
	v_mfma_f32_16x16x32_bf16 v[92:95], v[194:197], v[166:169], v[92:95]
	v_mfma_f32_16x16x32_bf16 v[88:91], v[202:205], v[166:169], v[88:91]
	v_mfma_f32_16x16x32_bf16 v[76:79], v[194:197], v[178:181], v[76:79]
	v_mfma_f32_16x16x32_bf16 v[72:75], v[202:205], v[178:181], v[72:75]
	v_mfma_f32_16x16x32_bf16 v[68:71], v[194:197], v[186:189], v[68:71]
	v_mfma_f32_16x16x32_bf16 v[64:67], v[202:205], v[186:189], v[64:67]
	v_mfma_f32_16x16x32_bf16 v[108:111], v[198:201], v[162:165], v[108:111]
	v_mfma_f32_16x16x32_bf16 v[104:107], v[206:209], v[162:165], v[104:107]
	v_mfma_f32_16x16x32_bf16 v[92:95], v[198:201], v[170:173], v[92:95]
	v_mfma_f32_16x16x32_bf16 v[88:91], v[206:209], v[170:173], v[88:91]
	v_mfma_f32_16x16x32_bf16 v[76:79], v[198:201], v[182:185], v[76:79]
	v_mfma_f32_16x16x32_bf16 v[72:75], v[206:209], v[182:185], v[72:75]
	v_mfma_f32_16x16x32_bf16 v[68:71], v[198:201], v[190:193], v[68:71]
	v_mfma_f32_16x16x32_bf16 v[64:67], v[206:209], v[190:193], v[64:67]
	s_setprio 0
	s_mov_b32 m0, s20
	v_lshl_add_u64 v[212:213], s[14:15], 0, v[132:133]
	s_barrier
	ds_read_b128 v[158:161], v141 offset:16384
	ds_read_b128 v[162:165], v141 offset:17408
	ds_read_b128 v[166:169], v141 offset:18432
	ds_read_b128 v[170:173], v141 offset:19456
	ds_read_b128 v[178:181], v141 offset:20480
	ds_read_b128 v[182:185], v141 offset:21504
	ds_read_b128 v[186:189], v141 offset:22528
	ds_read_b128 v[190:193], v141 offset:23552
	global_load_lds_dwordx4 v[212:213], off
	v_lshl_add_u64 v[214:215], s[14:15], 0, v[130:131]
	s_mov_b32 m0, s21
	s_nop 0
	global_load_lds_dwordx4 v[214:215], off
	s_barrier
	s_waitcnt lgkmcnt(0)
	s_setprio 1
	v_mfma_f32_16x16x32_bf16 v[60:63], v[142:145], v[158:161], v[60:63]
	v_mfma_f32_16x16x32_bf16 v[56:59], v[150:153], v[158:161], v[56:59]
	v_mfma_f32_16x16x32_bf16 v[52:55], v[142:145], v[166:169], v[52:55]
	v_mfma_f32_16x16x32_bf16 v[48:51], v[150:153], v[166:169], v[48:51]
	v_mfma_f32_16x16x32_bf16 v[36:39], v[142:145], v[178:181], v[36:39]
	v_mfma_f32_16x16x32_bf16 v[32:35], v[150:153], v[178:181], v[32:35]
	v_mfma_f32_16x16x32_bf16 v[20:23], v[142:145], v[186:189], v[20:23]
	v_mfma_f32_16x16x32_bf16 v[16:19], v[150:153], v[186:189], v[16:19]
	v_mfma_f32_16x16x32_bf16 v[60:63], v[146:149], v[162:165], v[60:63]
	v_mfma_f32_16x16x32_bf16 v[56:59], v[154:157], v[162:165], v[56:59]
	v_mfma_f32_16x16x32_bf16 v[52:55], v[146:149], v[170:173], v[52:55]
	v_mfma_f32_16x16x32_bf16 v[48:51], v[154:157], v[170:173], v[48:51]
	v_mfma_f32_16x16x32_bf16 v[36:39], v[146:149], v[182:185], v[36:39]
	v_mfma_f32_16x16x32_bf16 v[32:35], v[154:157], v[182:185], v[32:35]
	v_mfma_f32_16x16x32_bf16 v[20:23], v[146:149], v[190:193], v[20:23]
	v_mfma_f32_16x16x32_bf16 v[16:19], v[154:157], v[190:193], v[16:19]
	s_setprio 0
	s_barrier
; #define PG8_STAGE(bufoff, gbase, voff) do { _Pragma("unroll") for (int _i = 0; _i < 2; ++_i) \
;         __builtin_amdgcn_global_load_lds((const unsigned*)((const char*)(gbase) + (voff)[_i]), (PG8_LAS unsigned*)(lds + (bufoff) + ldsw + _i * 8192), 16, 0, 0); } while (0)
; #define PG8_LDA(dst, b, h) do { _Pragma("unroll") for (int m = 0; m < 4; ++m) _Pragma("unroll") for (int k = 0; k < 2; ++k) dst[m][k] = *(const PG8_LAS bf16x8*)(lds + PG8_SA(b, h) + aoff + m * 2048 + k * 1024); } while (0)
; #define PG8_LDB(dst, b, h) do { _Pragma("unroll") for (int n = 0; n < 2; ++n) _Pragma("unroll") for (int k = 0; k < 2; ++k) dst[n][k] = *(const PG8_LAS bf16x8*)(lds + PG8_SB(b, h) + boff + n * 2048 + k * 1024); } while (0)
; #define PG8_MMA(ai, bj, At, Bt) do { __builtin_amdgcn_s_setprio(1); _Pragma("unroll") for (int m = 0; m < 4; ++m) _Pragma("unroll") for (int n = 0; n < 2; ++n) _Pragma("unroll") for (int k = 0; k < 2; ++k) \
;         acc[ai][bj][m][n] = __builtin_amdgcn_mfma_f32_16x16x32_bf16(Bt[n][k], At[m][k], acc[ai][bj][m][n], 0, 0, 0); __builtin_amdgcn_s_setprio(0); } while (0)
; #define PG8_WAIT_V(n) asm volatile("s_waitcnt vmcnt(" #n ")" ::: "memory")
; #define PG8_WAIT_L(n) asm volatile("s_waitcnt lgkmcnt(" #n ")" ::: "memory")
; #define PG8_BAR __builtin_amdgcn_s_barrier()
; #define PG8_SCHED __builtin_amdgcn_sched_barrier(0)
; template <class Epi, class Sched>
; __device__ __forceinline__ void gemm_phase(PG8_LAS unsigned char* lds, const Gemm g, const Sched& S, const Epi& E) {
;     ...
;             PG8_STAGE(PG8_SB(0, 1), b2 + hstep, voffB);
;             PG8_WAIT_V(6); PG8_BAR; PG8_MMA(1, 1, At, B1); PG8_BAR;
;             PG8_LDB(B0, 1, 0); PG8_SCHED; PG8_LDA(At, 1, 0); PG8_STAGE(PG8_SA(0, 1), a2 + hstep, voffA);
;             PG8_WAIT_L(8); PG8_BAR; PG8_WAIT_L(0); PG8_MMA(0, 0, At, B0); PG8_BAR; PG8_SCHED;
;             PG8_LDB(B1, 1, 1); PG8_STAGE(PG8_SB(1, 0), b3, voffB);
;             PG8_BAR; PG8_WAIT_L(0); PG8_MMA(0, 1, At, B1); PG8_BAR;
	s_add_u32 s8, s12, 0xb0000
	s_addc_u32 s9, s13, 0
	s_add_i32 s46, s47, s18
	v_lshl_add_u64 v[142:143], s[8:9], 0, v[176:177]
	s_mov_b32 m0, s46
	s_nop 0
	global_load_lds_dwordx4 v[142:143], off
	v_lshl_add_u64 v[142:143], s[8:9], 0, v[128:129]
	s_add_i32 m0, s46, 0x2000
	s_nop 0
	global_load_lds_dwordx4 v[142:143], off
	s_waitcnt vmcnt(6)
	s_barrier
	s_setprio 1
	v_mfma_f32_16x16x32_bf16 v[44:47], v[194:197], v[158:161], v[44:47]
	v_mfma_f32_16x16x32_bf16 v[40:43], v[202:205], v[158:161], v[40:43]
	v_mfma_f32_16x16x32_bf16 v[28:31], v[194:197], v[166:169], v[28:31]
	v_mfma_f32_16x16x32_bf16 v[24:27], v[202:205], v[166:169], v[24:27]
	v_mfma_f32_16x16x32_bf16 v[12:15], v[194:197], v[178:181], v[12:15]
	v_mfma_f32_16x16x32_bf16 v[8:11], v[202:205], v[178:181], v[8:11]
	v_mfma_f32_16x16x32_bf16 v[4:7], v[194:197], v[186:189], v[4:7]
	v_mfma_f32_16x16x32_bf16 v[0:3], v[202:205], v[186:189], v[0:3]
	v_mfma_f32_16x16x32_bf16 v[44:47], v[198:201], v[162:165], v[44:47]
	v_mfma_f32_16x16x32_bf16 v[40:43], v[206:209], v[162:165], v[40:43]
	v_mfma_f32_16x16x32_bf16 v[28:31], v[198:201], v[170:173], v[28:31]
	v_mfma_f32_16x16x32_bf16 v[24:27], v[206:209], v[170:173], v[24:27]
	v_mfma_f32_16x16x32_bf16 v[12:15], v[198:201], v[182:185], v[12:15]
	v_mfma_f32_16x16x32_bf16 v[8:11], v[206:209], v[182:185], v[8:11]
	v_mfma_f32_16x16x32_bf16 v[4:7], v[198:201], v[190:193], v[4:7]
	v_mfma_f32_16x16x32_bf16 v[0:3], v[206:209], v[190:193], v[0:3]
	s_setprio 0
	s_add_i32 s46, 0, 0x18000
	v_add_u32_e32 v154, s46, v139
	s_barrier
	ds_read_b128 v[142:145], v154
	ds_read_b128 v[146:149], v154 offset:1024
	ds_read_b128 v[150:153], v154 offset:2048
	ds_read_b128 v[154:157], v154 offset:3072
	s_add_u32 s8, s14, 0xb0000
	s_addc_u32 s9, s15, 0
	s_mov_b32 m0, s22
	v_lshl_add_u64 v[194:195], s[8:9], 0, v[132:133]
	ds_read_b128 v[158:161], v141 offset:32768
	ds_read_b128 v[162:165], v141 offset:33792
	ds_read_b128 v[166:169], v141 offset:34816
	ds_read_b128 v[170:173], v141 offset:35840
	ds_read_b128 v[178:181], v141 offset:36864
	ds_read_b128 v[182:185], v141 offset:37888
	ds_read_b128 v[186:189], v141 offset:38912
	ds_read_b128 v[190:193], v141 offset:39936
	global_load_lds_dwordx4 v[194:195], off
	v_lshl_add_u64 v[194:195], s[8:9], 0, v[130:131]
	s_mov_b32 m0, s23
	s_nop 0
	global_load_lds_dwordx4 v[194:195], off
	s_waitcnt lgkmcnt(8)
	s_barrier
	s_waitcnt lgkmcnt(0)
	s_setprio 1
	v_mfma_f32_16x16x32_bf16 v[124:127], v[142:145], v[158:161], v[124:127]
	v_mfma_f32_16x16x32_bf16 v[120:123], v[150:153], v[158:161], v[120:123]
	v_mfma_f32_16x16x32_bf16 v[116:119], v[142:145], v[166:169], v[116:119]
	v_mfma_f32_16x16x32_bf16 v[112:115], v[150:153], v[166:169], v[112:115]
	v_mfma_f32_16x16x32_bf16 v[100:103], v[142:145], v[178:181], v[100:103]
	v_mfma_f32_16x16x32_bf16 v[96:99], v[150:153], v[178:181], v[96:99]
	v_mfma_f32_16x16x32_bf16 v[84:87], v[142:145], v[186:189], v[84:87]
	v_mfma_f32_16x16x32_bf16 v[80:83], v[150:153], v[186:189], v[80:83]
	v_mfma_f32_16x16x32_bf16 v[124:127], v[146:149], v[162:165], v[124:127]
	v_mfma_f32_16x16x32_bf16 v[120:123], v[154:157], v[162:165], v[120:123]
	v_mfma_f32_16x16x32_bf16 v[116:119], v[146:149], v[170:173], v[116:119]
	v_mfma_f32_16x16x32_bf16 v[112:115], v[154:157], v[170:173], v[112:115]
	v_mfma_f32_16x16x32_bf16 v[100:103], v[146:149], v[182:185], v[100:103]
	v_mfma_f32_16x16x32_bf16 v[96:99], v[154:157], v[182:185], v[96:99]
	v_mfma_f32_16x16x32_bf16 v[84:87], v[146:149], v[190:193], v[84:87]
	v_mfma_f32_16x16x32_bf16 v[80:83], v[154:157], v[190:193], v[80:83]
	s_setprio 0
	s_barrier
	s_add_i32 s14, 0, 0x1c000
	s_add_i32 s8, s46, s18
	v_add_u32_e32 v206, s14, v139
	v_lshl_add_u64 v[174:175], v[174:175], 0, s[86:87]
	s_mov_b32 m0, s8
	ds_read_b128 v[194:197], v206
	ds_read_b128 v[198:201], v206 offset:1024
	ds_read_b128 v[202:205], v206 offset:2048
	ds_read_b128 v[206:209], v206 offset:3072
	global_load_lds_dwordx4 v[174:175], off
	v_lshl_add_u64 v[174:175], v[210:211], 0, s[86:87]
	s_add_i32 m0, s8, 0x2000
	s_nop 0
	global_load_lds_dwordx4 v[174:175], off
	s_barrier
	s_waitcnt lgkmcnt(0)
	s_setprio 1
	v_mfma_f32_16x16x32_bf16 v[108:111], v[194:197], v[158:161], v[108:111]
	v_mfma_f32_16x16x32_bf16 v[104:107], v[202:205], v[158:161], v[104:107]
	v_mfma_f32_16x16x32_bf16 v[92:95], v[194:197], v[166:169], v[92:95]
	v_mfma_f32_16x16x32_bf16 v[88:91], v[202:205], v[166:169], v[88:91]
	v_mfma_f32_16x16x32_bf16 v[76:79], v[194:197], v[178:181], v[76:79]
	v_mfma_f32_16x16x32_bf16 v[72:75], v[202:205], v[178:181], v[72:75]
	v_mfma_f32_16x16x32_bf16 v[68:71], v[194:197], v[186:189], v[68:71]
	v_mfma_f32_16x16x32_bf16 v[64:67], v[202:205], v[186:189], v[64:67]
	v_mfma_f32_16x16x32_bf16 v[108:111], v[198:201], v[162:165], v[108:111]
	v_mfma_f32_16x16x32_bf16 v[104:107], v[206:209], v[162:165], v[104:107]
	v_mfma_f32_16x16x32_bf16 v[92:95], v[198:201], v[170:173], v[92:95]
	v_mfma_f32_16x16x32_bf16 v[88:91], v[206:209], v[170:173], v[88:91]
	v_mfma_f32_16x16x32_bf16 v[76:79], v[198:201], v[182:185], v[76:79]
	v_mfma_f32_16x16x32_bf16 v[72:75], v[206:209], v[182:185], v[72:75]
	v_mfma_f32_16x16x32_bf16 v[68:71], v[198:201], v[190:193], v[68:71]
	v_mfma_f32_16x16x32_bf16 v[64:67], v[206:209], v[190:193], v[64:67]
	s_setprio 0
	s_mov_b32 m0, s27
	v_lshl_add_u64 v[174:175], v[212:213], 0, s[86:87]
	s_barrier
	ds_read_b128 v[158:161], v141 offset:49152
	ds_read_b128 v[162:165], v141 offset:50176
	ds_read_b128 v[166:169], v141 offset:51200
	ds_read_b128 v[170:173], v141 offset:52224
	ds_read_b128 v[178:181], v141 offset:53248
	ds_read_b128 v[182:185], v141 offset:54272
	ds_read_b128 v[186:189], v141 offset:55296
	ds_read_b128 v[190:193], v141 offset:56320
	global_load_lds_dwordx4 v[174:175], off
	v_lshl_add_u64 v[174:175], v[214:215], 0, s[86:87]
	s_mov_b32 m0, s28
	s_nop 0
	global_load_lds_dwordx4 v[174:175], off
	s_barrier
; #define PG8_STAGE(bufoff, gbase, voff) do { _Pragma("unroll") for (int _i = 0; _i < 2; ++_i) \
;         __builtin_amdgcn_global_load_lds((const unsigned*)((const char*)(gbase) + (voff)[_i]), (PG8_LAS unsigned*)(lds + (bufoff) + ldsw + _i * 8192), 16, 0, 0); } while (0)
; #define PG8_MMA(ai, bj, At, Bt) do { __builtin_amdgcn_s_setprio(1); _Pragma("unroll") for (int m = 0; m < 4; ++m) _Pragma("unroll") for (int n = 0; n < 2; ++n) _Pragma("unroll") for (int k = 0; k < 2; ++k) \
;         acc[ai][bj][m][n] = __builtin_amdgcn_mfma_f32_16x16x32_bf16(Bt[n][k], At[m][k], acc[ai][bj][m][n], 0, 0, 0); __builtin_amdgcn_s_setprio(0); } while (0)
; #define PG8_WAIT_V(n) asm volatile("s_waitcnt vmcnt(" #n ")" ::: "memory")
; #define PG8_WAIT_L(n) asm volatile("s_waitcnt lgkmcnt(" #n ")" ::: "memory")
; #define PG8_BAR __builtin_amdgcn_s_barrier()
; #define PG8_SCHED __builtin_amdgcn_sched_barrier(0)
; template <class Epi, class Sched>
; __device__ __forceinline__ void gemm_phase(PG8_LAS unsigned char* lds, const Gemm g, const Sched& S, const Epi& E) {
;     ...
;             PG8_BAR; PG8_WAIT_L(0); PG8_MMA(1, 0, At, B0); PG8_BAR; PG8_SCHED;
;             PG8_STAGE(PG8_SB(1, 1), b3 + hstep, voffB);
;             PG8_WAIT_V(6); PG8_BAR; PG8_MMA(1, 1, At, B1); PG8_BAR;
;         }
	s_waitcnt lgkmcnt(0)
	s_setprio 1
	v_mfma_f32_16x16x32_bf16 v[60:63], v[142:145], v[158:161], v[60:63]
	v_mfma_f32_16x16x32_bf16 v[56:59], v[150:153], v[158:161], v[56:59]
	v_mfma_f32_16x16x32_bf16 v[52:55], v[142:145], v[166:169], v[52:55]
	v_mfma_f32_16x16x32_bf16 v[48:51], v[150:153], v[166:169], v[48:51]
	v_mfma_f32_16x16x32_bf16 v[36:39], v[142:145], v[178:181], v[36:39]
	v_mfma_f32_16x16x32_bf16 v[32:35], v[150:153], v[178:181], v[32:35]
	v_mfma_f32_16x16x32_bf16 v[20:23], v[142:145], v[186:189], v[20:23]
	v_mfma_f32_16x16x32_bf16 v[16:19], v[150:153], v[186:189], v[16:19]
	v_mfma_f32_16x16x32_bf16 v[60:63], v[146:149], v[162:165], v[60:63]
	v_mfma_f32_16x16x32_bf16 v[56:59], v[154:157], v[162:165], v[56:59]
	v_mfma_f32_16x16x32_bf16 v[52:55], v[146:149], v[170:173], v[52:55]
	v_mfma_f32_16x16x32_bf16 v[48:51], v[154:157], v[170:173], v[48:51]
	v_mfma_f32_16x16x32_bf16 v[36:39], v[146:149], v[182:185], v[36:39]
	v_mfma_f32_16x16x32_bf16 v[32:35], v[154:157], v[182:185], v[32:35]
	v_mfma_f32_16x16x32_bf16 v[20:23], v[146:149], v[190:193], v[20:23]
	v_mfma_f32_16x16x32_bf16 v[16:19], v[154:157], v[190:193], v[16:19]
	s_setprio 0
	s_barrier
	s_add_u32 s8, s12, 0xb0080
	s_addc_u32 s9, s13, 0
	s_add_i32 s12, s14, s18
	v_lshl_add_u64 v[142:143], s[8:9], 0, v[176:177]
	s_mov_b32 m0, s12
	s_nop 0
	global_load_lds_dwordx4 v[142:143], off
	v_lshl_add_u64 v[142:143], s[8:9], 0, v[128:129]
	s_add_i32 m0, s12, 0x2000
	s_nop 0
	global_load_lds_dwordx4 v[142:143], off
	s_waitcnt vmcnt(6)
	s_barrier
	s_setprio 1
	v_mfma_f32_16x16x32_bf16 v[44:47], v[194:197], v[158:161], v[44:47]
	v_mfma_f32_16x16x32_bf16 v[40:43], v[202:205], v[158:161], v[40:43]
	v_mfma_f32_16x16x32_bf16 v[28:31], v[194:197], v[166:169], v[28:31]
	v_mfma_f32_16x16x32_bf16 v[24:27], v[202:205], v[166:169], v[24:27]
	v_mfma_f32_16x16x32_bf16 v[12:15], v[194:197], v[178:181], v[12:15]
	v_mfma_f32_16x16x32_bf16 v[8:11], v[202:205], v[178:181], v[8:11]
	v_mfma_f32_16x16x32_bf16 v[4:7], v[194:197], v[186:189], v[4:7]
	v_mfma_f32_16x16x32_bf16 v[0:3], v[202:205], v[186:189], v[0:3]
	v_mfma_f32_16x16x32_bf16 v[44:47], v[198:201], v[162:165], v[44:47]
	v_mfma_f32_16x16x32_bf16 v[40:43], v[206:209], v[162:165], v[40:43]
	v_mfma_f32_16x16x32_bf16 v[28:31], v[198:201], v[170:173], v[28:31]
	v_mfma_f32_16x16x32_bf16 v[24:27], v[206:209], v[170:173], v[24:27]
	v_mfma_f32_16x16x32_bf16 v[12:15], v[198:201], v[182:185], v[12:15]
	v_mfma_f32_16x16x32_bf16 v[8:11], v[206:209], v[182:185], v[8:11]
	v_mfma_f32_16x16x32_bf16 v[4:7], v[198:201], v[190:193], v[4:7]
	v_mfma_f32_16x16x32_bf16 v[0:3], v[206:209], v[190:193], v[0:3]
	s_setprio 0
	s_add_i32 s45, s45, 2
	s_add_u32 s43, s43, 0x100
	s_addc_u32 s44, s44, 0
	s_cmp_gt_u32 s45, 41
	s_mov_b64 s[8:9], s[10:11]
	s_barrier
	s_cbranch_scc0 .LBB0_96
; __device__ __forceinline__ unsigned cvtpk(float lo, float hi) { const f32x2 v = (f32x2){lo, hi}; const bf16v2 b = __builtin_convertvector(v, bf16v2); return __builtin_bit_cast(unsigned, b); }
; #define PG8_WAIT_V(n) asm volatile("s_waitcnt vmcnt(" #n ")" ::: "memory")
; #define PG8_BAR __builtin_amdgcn_s_barrier()
; template <class Epi, class Sched>
; __device__ __forceinline__ void gemm_phase(PG8_LAS unsigned char* lds, const Gemm g, const Sched& S, const Epi& E) {
;     ...
;         if constexpr (!Epi::AFTER_DRAIN) { E(acc, cur, wr, wc, fr, fq); S.done(cur); }
;         if (!has_next) break;
; #pragma unroll
;         for (int a = 0; a < 2; ++a)
; #pragma unroll
;             for (int b = 0; b < 2; ++b)
; #pragma unroll
;                 for (int m = 0; m < 4; ++m)
; #pragma unroll
;                     for (int n = 0; n < 2; ++n) acc[a][b][m][n] = (f32x4){0.f, 0.f, 0.f, 0.f};
;         cur = nxt; cA = nA; cB = nB; ++ui;
;     }
;     PG8_WAIT_V(0);
;     if (wr == 0) PG8_BAR;
;     __device__ __forceinline__ void operator()(const f32x4 (&acc)[2][2][4][2], const pg8::Unit& u, int wr, int wc, int fr, int fq) const {
;         const int row0 = u.pm * 256 + wr * 64 + fr, col0 = u.pn * 256 + wc * 32 + 8 * fq;
; #pragma unroll
;         for (int ai = 0; ai < 2; ++ai)
; #pragma unroll
;             for (int m = 0; m < 4; ++m) { bf16_t* rowp = O + (size_t)(row0 + ai * 128 + m * 16) * ldc + col0;
; #pragma unroll
;                 for (int bj = 0; bj < 2; ++bj) { const f32x4 v0 = acc[ai][bj][m][0], v1 = acc[ai][bj][m][1];
;                     u32x4 w; w.x = cvtpk(v0[0], v0[1]); w.y = cvtpk(v0[2], v0[3]); w.z = cvtpk(v1[0], v1[1]); w.w = cvtpk(v1[2], v1[3]);
;                     *(u32x4*)(rowp + bj * 128) = w; } }
;     }
	v_lshl_add_u32 v142, s29, 8, v138
	v_lshl_or_b32 v144, s34, 8, v140
	v_ashrrev_i32_e32 v143, 31, v142
	v_readlane_b32 s8, v253, 18
	v_cvt_pk_bf16_f32 v108, v108, v109
	v_cvt_pk_bf16_f32 v109, v110, v111
	v_cvt_pk_bf16_f32 v110, v104, v105
	v_or_b32_e32 v104, 16, v142
	v_cvt_pk_bf16_f32 v92, v92, v93
	v_cvt_pk_bf16_f32 v93, v94, v95
	v_cvt_pk_bf16_f32 v94, v88, v89
	v_or_b32_e32 v88, 32, v142
	v_cvt_pk_bf16_f32 v76, v76, v77
	v_cvt_pk_bf16_f32 v77, v78, v79
	v_cvt_pk_bf16_f32 v78, v72, v73
	v_or_b32_e32 v72, 48, v142
	v_ashrrev_i32_e32 v145, 31, v144
	v_lshlrev_b64 v[146:147], 11, v[142:143]
	v_readlane_b32 s9, v253, 19
	v_ashrrev_i32_e32 v105, 31, v104
	v_ashrrev_i32_e32 v89, 31, v88
	v_ashrrev_i32_e32 v73, 31, v72
	v_lshl_add_u64 v[146:147], s[8:9], 0, v[146:147]
	v_lshlrev_b64 v[144:145], 1, v[144:145]
	v_lshlrev_b64 v[104:105], 11, v[104:105]
	v_lshlrev_b64 v[88:89], 11, v[88:89]
	v_lshlrev_b64 v[72:73], 11, v[72:73]
	v_lshl_add_u64 v[146:147], v[146:147], 0, v[144:145]
	v_lshl_add_u64 v[104:105], s[8:9], 0, v[104:105]
	v_lshl_add_u64 v[88:89], s[8:9], 0, v[88:89]
	v_lshl_add_u64 v[72:73], s[8:9], 0, v[72:73]
	s_mov_b64 s[8:9], 0x40000
	v_cvt_pk_bf16_f32 v68, v68, v69
	v_cvt_pk_bf16_f32 v69, v70, v71
	v_cvt_pk_bf16_f32 v70, v64, v65
	v_lshl_add_u64 v[64:65], v[146:147], 0, s[8:9]
	v_cvt_pk_bf16_f32 v60, v60, v61
	v_cvt_pk_bf16_f32 v61, v62, v63
	v_cvt_pk_bf16_f32 v62, v56, v57
	v_add_co_u32_e32 v56, vcc, s2, v146
	v_cvt_pk_bf16_f32 v44, v44, v45
	v_cvt_pk_bf16_f32 v45, v46, v47
	v_cvt_pk_bf16_f32 v46, v40, v41
	v_cvt_pk_bf16_f32 v47, v42, v43
	s_mov_b64 s[8:9], 0x48000
	v_addc_co_u32_e32 v57, vcc, 0, v147, vcc
	global_store_dwordx4 v[64:65], v[44:47], off offset:256
	v_cvt_pk_bf16_f32 v28, v28, v29
	v_cvt_pk_bf16_f32 v29, v30, v31
	v_lshl_add_u64 v[44:45], v[146:147], 0, s[8:9]
	s_mov_b32 s8, 0x48000
	v_add_co_u32_e32 v46, vcc, s8, v146
	v_cvt_pk_bf16_f32 v30, v24, v25
	v_cvt_pk_bf16_f32 v31, v26, v27
	s_mov_b64 s[8:9], 0x50000
	v_addc_co_u32_e32 v47, vcc, 0, v147, vcc
	global_store_dwordx4 v[44:45], v[28:31], off offset:256
	v_cvt_pk_bf16_f32 v12, v12, v13
	v_cvt_pk_bf16_f32 v13, v14, v15
	v_lshl_add_u64 v[28:29], v[146:147], 0, s[8:9]
	s_mov_b32 s8, 0x50000
	v_add_co_u32_e32 v30, vcc, s8, v146
	v_cvt_pk_bf16_f32 v14, v8, v9
	v_cvt_pk_bf16_f32 v15, v10, v11
	s_mov_b64 s[8:9], 0x58000
	v_cvt_pk_bf16_f32 v111, v106, v107
	v_addc_co_u32_e32 v31, vcc, 0, v147, vcc
	global_store_dwordx4 v[28:29], v[12:15], off offset:256
	global_store_dwordx4 v[146:147], v[108:111], off offset:256
	v_cvt_pk_bf16_f32 v95, v90, v91
	v_lshl_add_u64 v[12:13], v[146:147], 0, s[8:9]
	s_mov_b32 s8, 0x58000
	v_lshl_add_u64 v[108:109], v[104:105], 0, v[144:145]
	v_add_co_u32_e32 v14, vcc, s8, v146
	global_store_dwordx4 v[108:109], v[92:95], off offset:256
	v_cvt_pk_bf16_f32 v79, v74, v75
	v_addc_co_u32_e32 v15, vcc, 0, v147, vcc
	v_lshl_add_u64 v[92:93], v[88:89], 0, v[144:145]
	v_cvt_pk_bf16_f32 v124, v124, v125
	v_cvt_pk_bf16_f32 v125, v126, v127
	v_cvt_pk_bf16_f32 v126, v120, v121
	v_cvt_pk_bf16_f32 v127, v122, v123
	v_cvt_pk_bf16_f32 v104, v116, v117
	v_cvt_pk_bf16_f32 v105, v118, v119
	v_cvt_pk_bf16_f32 v106, v112, v113
	v_cvt_pk_bf16_f32 v107, v114, v115
	v_cvt_pk_bf16_f32 v88, v100, v101
	v_cvt_pk_bf16_f32 v89, v102, v103
	v_cvt_pk_bf16_f32 v90, v96, v97
	v_cvt_pk_bf16_f32 v91, v98, v99
	global_store_dwordx4 v[92:93], v[76:79], off offset:256
	v_cvt_pk_bf16_f32 v74, v80, v81
	v_cvt_pk_bf16_f32 v75, v82, v83
	v_lshl_add_u64 v[76:77], v[72:73], 0, v[144:145]
	v_cvt_pk_bf16_f32 v72, v84, v85
	v_cvt_pk_bf16_f32 v73, v86, v87
	v_cvt_pk_bf16_f32 v71, v66, v67
	v_cvt_pk_bf16_f32 v63, v58, v59
	v_cvt_pk_bf16_f32 v40, v52, v53
	v_cvt_pk_bf16_f32 v41, v54, v55
	v_cvt_pk_bf16_f32 v42, v48, v49
	v_cvt_pk_bf16_f32 v43, v50, v51
	v_cvt_pk_bf16_f32 v24, v36, v37
	v_cvt_pk_bf16_f32 v25, v38, v39
	v_cvt_pk_bf16_f32 v26, v32, v33
	v_cvt_pk_bf16_f32 v27, v34, v35
	v_cvt_pk_bf16_f32 v8, v20, v21
	v_cvt_pk_bf16_f32 v9, v22, v23
	v_cvt_pk_bf16_f32 v10, v16, v17
	v_cvt_pk_bf16_f32 v11, v18, v19
	v_cvt_pk_bf16_f32 v4, v4, v5
	v_cvt_pk_bf16_f32 v5, v6, v7
	v_cvt_pk_bf16_f32 v6, v0, v1
	v_cvt_pk_bf16_f32 v7, v2, v3
	s_and_b64 vcc, exec, s[38:39]
	s_mov_b32 s34, s40
	s_mov_b32 s29, s41
	s_mov_b64 s[10:11], s[4:5]
	s_mov_b64 s[8:9], s[0:1]
	global_store_dwordx4 v[146:147], v[124:127], off
	global_store_dwordx4 v[108:109], v[104:107], off
	global_store_dwordx4 v[92:93], v[88:91], off
	global_store_dwordx4 v[76:77], v[72:75], off
	global_store_dwordx4 v[76:77], v[68:71], off offset:256
	global_store_dwordx4 v[56:57], v[60:63], off
	global_store_dwordx4 v[46:47], v[40:43], off
	global_store_dwordx4 v[30:31], v[24:27], off
	global_store_dwordx4 v[14:15], v[8:11], off
	global_store_dwordx4 v[12:13], v[4:7], off offset:256
	s_cbranch_vccz .LBB0_89
	s_waitcnt vmcnt(0)
	s_cmpk_gt_u32 s17, 0xff
	v_readlane_b32 s2, v254, 59
	s_cbranch_scc1 .LBB0_100
	s_barrier

; #define PG8_STAGE(bufoff, gbase, voff) do { _Pragma("unroll") for (int _i = 0; _i < 2; ++_i) \
;         __builtin_amdgcn_global_load_lds((const unsigned*)((const char*)(gbase) + (voff)[_i]), (PG8_LAS unsigned*)(lds + (bufoff) + ldsw + _i * 8192), 16, 0, 0); } while (0)
; #define PG8_LDA(dst, b, h) do { _Pragma("unroll") for (int m = 0; m < 4; ++m) _Pragma("unroll") for (int k = 0; k < 2; ++k) dst[m][k] = *(const PG8_LAS bf16x8*)(lds + PG8_SA(b, h) + aoff + m * 2048 + k * 1024); } while (0)
; #define PG8_LDB(dst, b, h) do { _Pragma("unroll") for (int n = 0; n < 2; ++n) _Pragma("unroll") for (int k = 0; k < 2; ++k) dst[n][k] = *(const PG8_LAS bf16x8*)(lds + PG8_SB(b, h) + boff + n * 2048 + k * 1024); } while (0)
; #define PG8_MMA(ai, bj, At, Bt) do { __builtin_amdgcn_s_setprio(1); _Pragma("unroll") for (int m = 0; m < 4; ++m) _Pragma("unroll") for (int n = 0; n < 2; ++n) _Pragma("unroll") for (int k = 0; k < 2; ++k) \
;         acc[ai][bj][m][n] = __builtin_amdgcn_mfma_f32_16x16x32_bf16(Bt[n][k], At[m][k], acc[ai][bj][m][n], 0, 0, 0); __builtin_amdgcn_s_setprio(0); } while (0)
; #define PG8_WAIT_L(n) asm volatile("s_waitcnt lgkmcnt(" #n ")" ::: "memory")
; #define PG8_BAR __builtin_amdgcn_s_barrier()
; #define PG8_SCHED __builtin_amdgcn_sched_barrier(0)
; template <class Epi, class Sched>
; __device__ __forceinline__ void gemm_phase(PG8_LAS unsigned char* lds, const Gemm g, const Sched& S, const Epi& E) {
;     ...
;         for (int t = 0; t < nt; t += 2) {
;             const bool last = (t == nt - 2);
;             const char* a1 = cA + (size_t)(t + 1) * kstep;
;             const char* a2 = last ? nA : cA + (size_t)(t + 2) * kstep; const char* b2 = last ? nB : cB + (size_t)(t + 2) * kstep;
;             const char* a3 = a2 + kstep; const char* b3 = b2 + kstep;
;             if (last && has_next) S.a_ready(nxt);
;             PG8_LDB(B0, 0, 0); PG8_SCHED; PG8_LDA(At, 0, 0); PG8_STAGE(PG8_SA(1, 1), a1 + hstep, voffA);
;             PG8_WAIT_L(8); PG8_BAR; PG8_WAIT_L(0); PG8_MMA(0, 0, At, B0); PG8_BAR; PG8_SCHED;
;             PG8_LDB(B1, 0, 1); PG8_STAGE(PG8_SB(0, 0), b2, voffB);
;             PG8_BAR; PG8_WAIT_L(0); PG8_MMA(0, 1, At, B1); PG8_BAR;
;             PG8_LDA(At, 0, 1); PG8_STAGE(PG8_SA(0, 0), a2, voffA);
;             PG8_BAR; PG8_WAIT_L(0); PG8_MMA(1, 0, At, B0); PG8_BAR; PG8_SCHED;
.LBB0_114:
	s_add_u32 s14, s12, 0xfffc0080
	s_addc_u32 s15, s13, -1
	s_add_i32 s46, 0, 0x10000
	v_add_u32_e32 v154, s46, v143
	ds_read_b128 v[138:141], v154
	ds_read_b128 v[146:149], v154 offset:1024
	ds_read_b128 v[150:153], v154 offset:2048
	ds_read_b128 v[154:157], v154 offset:3072
	s_cmp_eq_u32 s45, 12
	s_cselect_b32 s17, s5, s15
	s_cselect_b32 s16, s40, s14
	s_cselect_b32 s15, s1, s44
	s_cselect_b32 s14, s41, s43
	v_lshl_add_u64 v[174:175], s[12:13], 0, v[134:135]
	s_add_i32 m0, s11, 0xc000
	ds_read_b128 v[158:161], v145
	ds_read_b128 v[162:165], v145 offset:1024
	ds_read_b128 v[166:169], v145 offset:2048
	ds_read_b128 v[170:173], v145 offset:3072
	ds_read_b128 v[178:181], v145 offset:4096
	ds_read_b128 v[182:185], v145 offset:5120
	ds_read_b128 v[186:189], v145 offset:6144
	ds_read_b128 v[190:193], v145 offset:7168
	global_load_lds_dwordx4 v[174:175], off
	v_lshl_add_u64 v[174:175], s[12:13], 0, v[136:137]
	s_add_i32 m0, s11, 0xe000
	s_nop 0
	global_load_lds_dwordx4 v[174:175], off
	s_waitcnt lgkmcnt(8)
	s_barrier
	s_waitcnt lgkmcnt(0)
	s_setprio 1
	v_mfma_f32_16x16x32_bf16 v[124:127], v[138:141], v[158:161], v[124:127]
	v_mfma_f32_16x16x32_bf16 v[116:119], v[150:153], v[158:161], v[116:119]
	v_mfma_f32_16x16x32_bf16 v[108:111], v[138:141], v[166:169], v[108:111]
	v_mfma_f32_16x16x32_bf16 v[100:103], v[150:153], v[166:169], v[100:103]
	v_mfma_f32_16x16x32_bf16 v[92:95], v[138:141], v[178:181], v[92:95]
	v_mfma_f32_16x16x32_bf16 v[84:87], v[150:153], v[178:181], v[84:87]
	v_mfma_f32_16x16x32_bf16 v[76:79], v[138:141], v[186:189], v[76:79]
	v_mfma_f32_16x16x32_bf16 v[68:71], v[150:153], v[186:189], v[68:71]
	v_mfma_f32_16x16x32_bf16 v[124:127], v[146:149], v[162:165], v[124:127]
	v_mfma_f32_16x16x32_bf16 v[116:119], v[154:157], v[162:165], v[116:119]
	v_mfma_f32_16x16x32_bf16 v[108:111], v[146:149], v[170:173], v[108:111]
	v_mfma_f32_16x16x32_bf16 v[100:103], v[154:157], v[170:173], v[100:103]
	v_mfma_f32_16x16x32_bf16 v[92:95], v[146:149], v[182:185], v[92:95]
	v_mfma_f32_16x16x32_bf16 v[84:87], v[154:157], v[182:185], v[84:87]
	v_mfma_f32_16x16x32_bf16 v[76:79], v[146:149], v[190:193], v[76:79]
	v_mfma_f32_16x16x32_bf16 v[68:71], v[154:157], v[190:193], v[68:71]
	s_setprio 0
	s_barrier
	s_add_i32 s48, 0, 0x14000
	v_add_u32_e32 v174, s48, v143
	s_add_i32 s46, s46, s20
	ds_read_b128 v[194:197], v174
	ds_read_b128 v[198:201], v174 offset:1024
	ds_read_b128 v[202:205], v174 offset:2048
	ds_read_b128 v[206:209], v174 offset:3072
	v_lshl_add_u64 v[174:175], s[14:15], 0, v[176:177]
	s_mov_b32 m0, s46
	v_lshl_add_u64 v[210:211], s[14:15], 0, v[128:129]
	global_load_lds_dwordx4 v[174:175], off
	s_add_i32 m0, s46, 0x2000
	s_nop 0
	global_load_lds_dwordx4 v[210:211], off
	s_barrier
	s_waitcnt lgkmcnt(0)
	s_setprio 1
	v_mfma_f32_16x16x32_bf16 v[120:123], v[194:197], v[158:161], v[120:123]
	v_mfma_f32_16x16x32_bf16 v[112:115], v[202:205], v[158:161], v[112:115]
	v_mfma_f32_16x16x32_bf16 v[104:107], v[194:197], v[166:169], v[104:107]
	v_mfma_f32_16x16x32_bf16 v[96:99], v[202:205], v[166:169], v[96:99]
	v_mfma_f32_16x16x32_bf16 v[88:91], v[194:197], v[178:181], v[88:91]
	v_mfma_f32_16x16x32_bf16 v[80:83], v[202:205], v[178:181], v[80:83]
	v_mfma_f32_16x16x32_bf16 v[72:75], v[194:197], v[186:189], v[72:75]
	v_mfma_f32_16x16x32_bf16 v[64:67], v[202:205], v[186:189], v[64:67]
	v_mfma_f32_16x16x32_bf16 v[120:123], v[198:201], v[162:165], v[120:123]
	v_mfma_f32_16x16x32_bf16 v[112:115], v[206:209], v[162:165], v[112:115]
	v_mfma_f32_16x16x32_bf16 v[104:107], v[198:201], v[170:173], v[104:107]
	v_mfma_f32_16x16x32_bf16 v[96:99], v[206:209], v[170:173], v[96:99]
	v_mfma_f32_16x16x32_bf16 v[88:91], v[198:201], v[182:185], v[88:91]
	v_mfma_f32_16x16x32_bf16 v[80:83], v[206:209], v[182:185], v[80:83]
	v_mfma_f32_16x16x32_bf16 v[72:75], v[198:201], v[190:193], v[72:75]
	v_mfma_f32_16x16x32_bf16 v[64:67], v[206:209], v[190:193], v[64:67]
	s_setprio 0
	s_mov_b32 m0, s11
	v_lshl_add_u64 v[212:213], s[16:17], 0, v[132:133]
	s_barrier
	ds_read_b128 v[158:161], v145 offset:16384
	ds_read_b128 v[162:165], v145 offset:17408
	ds_read_b128 v[166:169], v145 offset:18432
	ds_read_b128 v[170:173], v145 offset:19456
	ds_read_b128 v[178:181], v145 offset:20480
	ds_read_b128 v[182:185], v145 offset:21504
	ds_read_b128 v[186:189], v145 offset:22528
	ds_read_b128 v[190:193], v145 offset:23552
	global_load_lds_dwordx4 v[212:213], off
	v_lshl_add_u64 v[214:215], s[16:17], 0, v[130:131]
	s_mov_b32 m0, s22
	s_nop 0
	global_load_lds_dwordx4 v[214:215], off
	s_barrier
	s_waitcnt lgkmcnt(0)
	s_setprio 1
	v_mfma_f32_16x16x32_bf16 v[60:63], v[138:141], v[158:161], v[60:63]
	v_mfma_f32_16x16x32_bf16 v[52:55], v[150:153], v[158:161], v[52:55]
	v_mfma_f32_16x16x32_bf16 v[44:47], v[138:141], v[166:169], v[44:47]
	v_mfma_f32_16x16x32_bf16 v[36:39], v[150:153], v[166:169], v[36:39]
	v_mfma_f32_16x16x32_bf16 v[28:31], v[138:141], v[178:181], v[28:31]
	v_mfma_f32_16x16x32_bf16 v[20:23], v[150:153], v[178:181], v[20:23]
	v_mfma_f32_16x16x32_bf16 v[12:15], v[138:141], v[186:189], v[12:15]
	v_mfma_f32_16x16x32_bf16 v[4:7], v[150:153], v[186:189], v[4:7]
	v_mfma_f32_16x16x32_bf16 v[60:63], v[146:149], v[162:165], v[60:63]
	v_mfma_f32_16x16x32_bf16 v[52:55], v[154:157], v[162:165], v[52:55]
	v_mfma_f32_16x16x32_bf16 v[44:47], v[146:149], v[170:173], v[44:47]
	v_mfma_f32_16x16x32_bf16 v[36:39], v[154:157], v[170:173], v[36:39]
	v_mfma_f32_16x16x32_bf16 v[28:31], v[146:149], v[182:185], v[28:31]
	v_mfma_f32_16x16x32_bf16 v[20:23], v[154:157], v[182:185], v[20:23]
	v_mfma_f32_16x16x32_bf16 v[12:15], v[146:149], v[190:193], v[12:15]
	v_mfma_f32_16x16x32_bf16 v[4:7], v[154:157], v[190:193], v[4:7]
	s_setprio 0
	s_barrier
; #define PG8_STAGE(bufoff, gbase, voff) do { _Pragma("unroll") for (int _i = 0; _i < 2; ++_i) \
;         __builtin_amdgcn_global_load_lds((const unsigned*)((const char*)(gbase) + (voff)[_i]), (PG8_LAS unsigned*)(lds + (bufoff) + ldsw + _i * 8192), 16, 0, 0); } while (0)
; #define PG8_LDA(dst, b, h) do { _Pragma("unroll") for (int m = 0; m < 4; ++m) _Pragma("unroll") for (int k = 0; k < 2; ++k) dst[m][k] = *(const PG8_LAS bf16x8*)(lds + PG8_SA(b, h) + aoff + m * 2048 + k * 1024); } while (0)
; #define PG8_LDB(dst, b, h) do { _Pragma("unroll") for (int n = 0; n < 2; ++n) _Pragma("unroll") for (int k = 0; k < 2; ++k) dst[n][k] = *(const PG8_LAS bf16x8*)(lds + PG8_SB(b, h) + boff + n * 2048 + k * 1024); } while (0)
; #define PG8_MMA(ai, bj, At, Bt) do { __builtin_amdgcn_s_setprio(1); _Pragma("unroll") for (int m = 0; m < 4; ++m) _Pragma("unroll") for (int n = 0; n < 2; ++n) _Pragma("unroll") for (int k = 0; k < 2; ++k) \
;         acc[ai][bj][m][n] = __builtin_amdgcn_mfma_f32_16x16x32_bf16(Bt[n][k], At[m][k], acc[ai][bj][m][n], 0, 0, 0); __builtin_amdgcn_s_setprio(0); } while (0)
; #define PG8_WAIT_V(n) asm volatile("s_waitcnt vmcnt(" #n ")" ::: "memory")
; #define PG8_WAIT_L(n) asm volatile("s_waitcnt lgkmcnt(" #n ")" ::: "memory")
; #define PG8_BAR __builtin_amdgcn_s_barrier()
; #define PG8_SCHED __builtin_amdgcn_sched_barrier(0)
; template <class Epi, class Sched>
; __device__ __forceinline__ void gemm_phase(PG8_LAS unsigned char* lds, const Gemm g, const Sched& S, const Epi& E) {
;     ...
;             PG8_STAGE(PG8_SB(0, 1), b2 + hstep, voffB);
;             PG8_WAIT_V(6); PG8_BAR; PG8_MMA(1, 1, At, B1); PG8_BAR;
;             PG8_LDB(B0, 1, 0); PG8_SCHED; PG8_LDA(At, 1, 0); PG8_STAGE(PG8_SA(0, 1), a2 + hstep, voffA);
;             PG8_WAIT_L(8); PG8_BAR; PG8_WAIT_L(0); PG8_MMA(0, 0, At, B0); PG8_BAR; PG8_SCHED;
;             PG8_LDB(B1, 1, 1); PG8_STAGE(PG8_SB(1, 0), b3, voffB);
;             PG8_BAR; PG8_WAIT_L(0); PG8_MMA(0, 1, At, B1); PG8_BAR;
;             PG8_LDA(At, 1, 1); PG8_STAGE(PG8_SA(1, 0), a3, voffA);
	s_add_u32 s46, s14, 0x40000
	s_addc_u32 s47, s15, 0
	s_add_i32 s48, s48, s20
	v_lshl_add_u64 v[138:139], s[46:47], 0, v[176:177]
	s_mov_b32 m0, s48
	s_nop 0
	global_load_lds_dwordx4 v[138:139], off
	v_lshl_add_u64 v[138:139], s[46:47], 0, v[128:129]
	s_add_i32 m0, s48, 0x2000
	s_nop 0
	global_load_lds_dwordx4 v[138:139], off
	s_waitcnt vmcnt(6)
	s_barrier
	s_setprio 1
	v_mfma_f32_16x16x32_bf16 v[56:59], v[194:197], v[158:161], v[56:59]
	v_mfma_f32_16x16x32_bf16 v[48:51], v[202:205], v[158:161], v[48:51]
	v_mfma_f32_16x16x32_bf16 v[40:43], v[194:197], v[166:169], v[40:43]
	v_mfma_f32_16x16x32_bf16 v[32:35], v[202:205], v[166:169], v[32:35]
	v_mfma_f32_16x16x32_bf16 v[24:27], v[194:197], v[178:181], v[24:27]
	v_mfma_f32_16x16x32_bf16 v[16:19], v[202:205], v[178:181], v[16:19]
	v_mfma_f32_16x16x32_bf16 v[8:11], v[194:197], v[186:189], v[8:11]
	v_mfma_f32_16x16x32_bf16 v[0:3], v[202:205], v[186:189], v[0:3]
	v_mfma_f32_16x16x32_bf16 v[56:59], v[198:201], v[162:165], v[56:59]
	v_mfma_f32_16x16x32_bf16 v[48:51], v[206:209], v[162:165], v[48:51]
	v_mfma_f32_16x16x32_bf16 v[40:43], v[198:201], v[170:173], v[40:43]
	v_mfma_f32_16x16x32_bf16 v[32:35], v[206:209], v[170:173], v[32:35]
	v_mfma_f32_16x16x32_bf16 v[24:27], v[198:201], v[182:185], v[24:27]
	v_mfma_f32_16x16x32_bf16 v[16:19], v[206:209], v[182:185], v[16:19]
	v_mfma_f32_16x16x32_bf16 v[8:11], v[198:201], v[190:193], v[8:11]
	v_mfma_f32_16x16x32_bf16 v[0:3], v[206:209], v[190:193], v[0:3]
	s_setprio 0
	s_add_i32 s46, 0, 0x18000
	v_add_u32_e32 v154, s46, v143
	s_barrier
	ds_read_b128 v[138:141], v154
	ds_read_b128 v[146:149], v154 offset:1024
	ds_read_b128 v[150:153], v154 offset:2048
	ds_read_b128 v[154:157], v154 offset:3072
	s_add_u32 s16, s16, 0x40000
	s_addc_u32 s17, s17, 0
	s_mov_b32 m0, s23
	v_lshl_add_u64 v[194:195], s[16:17], 0, v[132:133]
	ds_read_b128 v[158:161], v145 offset:32768
	ds_read_b128 v[162:165], v145 offset:33792
	ds_read_b128 v[166:169], v145 offset:34816
	ds_read_b128 v[170:173], v145 offset:35840
	ds_read_b128 v[178:181], v145 offset:36864
	ds_read_b128 v[182:185], v145 offset:37888
	ds_read_b128 v[186:189], v145 offset:38912
	ds_read_b128 v[190:193], v145 offset:39936
	global_load_lds_dwordx4 v[194:195], off
	v_lshl_add_u64 v[194:195], s[16:17], 0, v[130:131]
	s_mov_b32 m0, s26
	s_nop 0
	global_load_lds_dwordx4 v[194:195], off
	s_waitcnt lgkmcnt(8)
	s_barrier
	s_waitcnt lgkmcnt(0)
	s_setprio 1
	v_mfma_f32_16x16x32_bf16 v[124:127], v[138:141], v[158:161], v[124:127]
	v_mfma_f32_16x16x32_bf16 v[116:119], v[150:153], v[158:161], v[116:119]
	v_mfma_f32_16x16x32_bf16 v[108:111], v[138:141], v[166:169], v[108:111]
	v_mfma_f32_16x16x32_bf16 v[100:103], v[150:153], v[166:169], v[100:103]
	v_mfma_f32_16x16x32_bf16 v[92:95], v[138:141], v[178:181], v[92:95]
	v_mfma_f32_16x16x32_bf16 v[84:87], v[150:153], v[178:181], v[84:87]
	v_mfma_f32_16x16x32_bf16 v[76:79], v[138:141], v[186:189], v[76:79]
	v_mfma_f32_16x16x32_bf16 v[68:71], v[150:153], v[186:189], v[68:71]
	v_mfma_f32_16x16x32_bf16 v[124:127], v[146:149], v[162:165], v[124:127]
	v_mfma_f32_16x16x32_bf16 v[116:119], v[154:157], v[162:165], v[116:119]
	v_mfma_f32_16x16x32_bf16 v[108:111], v[146:149], v[170:173], v[108:111]
	v_mfma_f32_16x16x32_bf16 v[100:103], v[154:157], v[170:173], v[100:103]
	v_mfma_f32_16x16x32_bf16 v[92:95], v[146:149], v[182:185], v[92:95]
	v_mfma_f32_16x16x32_bf16 v[84:87], v[154:157], v[182:185], v[84:87]
	v_mfma_f32_16x16x32_bf16 v[76:79], v[146:149], v[190:193], v[76:79]
	v_mfma_f32_16x16x32_bf16 v[68:71], v[154:157], v[190:193], v[68:71]
	s_setprio 0
	s_barrier
	s_add_i32 s16, 0, 0x1c000
	s_add_i32 s17, s46, s20
	v_add_u32_e32 v206, s16, v143
	v_lshl_add_u64 v[174:175], v[174:175], 0, s[86:87]
	s_mov_b32 m0, s17
	ds_read_b128 v[194:197], v206
	ds_read_b128 v[198:201], v206 offset:1024
	ds_read_b128 v[202:205], v206 offset:2048
	ds_read_b128 v[206:209], v206 offset:3072
	global_load_lds_dwordx4 v[174:175], off
	v_lshl_add_u64 v[174:175], v[210:211], 0, s[86:87]
	s_add_i32 m0, s17, 0x2000
	s_nop 0
	global_load_lds_dwordx4 v[174:175], off
	s_barrier
	s_waitcnt lgkmcnt(0)
	s_setprio 1
	v_mfma_f32_16x16x32_bf16 v[120:123], v[194:197], v[158:161], v[120:123]
	v_mfma_f32_16x16x32_bf16 v[112:115], v[202:205], v[158:161], v[112:115]
	v_mfma_f32_16x16x32_bf16 v[104:107], v[194:197], v[166:169], v[104:107]
	v_mfma_f32_16x16x32_bf16 v[96:99], v[202:205], v[166:169], v[96:99]
	v_mfma_f32_16x16x32_bf16 v[88:91], v[194:197], v[178:181], v[88:91]
	v_mfma_f32_16x16x32_bf16 v[80:83], v[202:205], v[178:181], v[80:83]
	v_mfma_f32_16x16x32_bf16 v[72:75], v[194:197], v[186:189], v[72:75]
	v_mfma_f32_16x16x32_bf16 v[64:67], v[202:205], v[186:189], v[64:67]
	v_mfma_f32_16x16x32_bf16 v[120:123], v[198:201], v[162:165], v[120:123]
	v_mfma_f32_16x16x32_bf16 v[112:115], v[206:209], v[162:165], v[112:115]
	v_mfma_f32_16x16x32_bf16 v[104:107], v[198:201], v[170:173], v[104:107]
	v_mfma_f32_16x16x32_bf16 v[96:99], v[206:209], v[170:173], v[96:99]
	v_mfma_f32_16x16x32_bf16 v[88:91], v[198:201], v[182:185], v[88:91]
	v_mfma_f32_16x16x32_bf16 v[80:83], v[206:209], v[182:185], v[80:83]
	v_mfma_f32_16x16x32_bf16 v[72:75], v[198:201], v[190:193], v[72:75]
	v_mfma_f32_16x16x32_bf16 v[64:67], v[206:209], v[190:193], v[64:67]
	s_setprio 0
	s_mov_b32 m0, s28
	v_lshl_add_u64 v[174:175], v[212:213], 0, s[86:87]
	s_barrier
	ds_read_b128 v[158:161], v145 offset:49152
	ds_read_b128 v[162:165], v145 offset:50176
	ds_read_b128 v[166:169], v145 offset:51200
	ds_read_b128 v[170:173], v145 offset:52224
	ds_read_b128 v[178:181], v145 offset:53248
	ds_read_b128 v[182:185], v145 offset:54272
	ds_read_b128 v[186:189], v145 offset:55296
	ds_read_b128 v[190:193], v145 offset:56320
	global_load_lds_dwordx4 v[174:175], off
	v_lshl_add_u64 v[174:175], v[214:215], 0, s[86:87]
	s_mov_b32 m0, s29
	s_nop 0
	global_load_lds_dwordx4 v[174:175], off
	s_barrier
; __device__ __forceinline__ unsigned cvtpk(float lo, float hi) { const f32x2 v = (f32x2){lo, hi}; const bf16v2 b = __builtin_convertvector(v, bf16v2); return __builtin_bit_cast(unsigned, b); }
; __device__ __forceinline__ float siluf_(float x) { return x * sigmoidf_(x); }
; #define PG8_STAGE(bufoff, gbase, voff) do { _Pragma("unroll") for (int _i = 0; _i < 2; ++_i) \
;         __builtin_amdgcn_global_load_lds((const unsigned*)((const char*)(gbase) + (voff)[_i]), (PG8_LAS unsigned*)(lds + (bufoff) + ldsw + _i * 8192), 16, 0, 0); } while (0)
; #define PG8_MMA(ai, bj, At, Bt) do { __builtin_amdgcn_s_setprio(1); _Pragma("unroll") for (int m = 0; m < 4; ++m) _Pragma("unroll") for (int n = 0; n < 2; ++n) _Pragma("unroll") for (int k = 0; k < 2; ++k) \
;         acc[ai][bj][m][n] = __builtin_amdgcn_mfma_f32_16x16x32_bf16(Bt[n][k], At[m][k], acc[ai][bj][m][n], 0, 0, 0); __builtin_amdgcn_s_setprio(0); } while (0)
; #define PG8_WAIT_V(n) asm volatile("s_waitcnt vmcnt(" #n ")" ::: "memory")
; #define PG8_WAIT_L(n) asm volatile("s_waitcnt lgkmcnt(" #n ")" ::: "memory")
; #define PG8_BAR __builtin_amdgcn_s_barrier()
; template <class Epi, class Sched>
; __device__ __forceinline__ void gemm_phase(PG8_LAS unsigned char* lds, const Gemm g, const Sched& S, const Epi& E) {
;     ...
;             PG8_BAR; PG8_WAIT_L(0); PG8_MMA(1, 0, At, B0); PG8_BAR; PG8_SCHED;
;             PG8_STAGE(PG8_SB(1, 1), b3 + hstep, voffB);
;             PG8_WAIT_V(6); PG8_BAR; PG8_MMA(1, 1, At, B1); PG8_BAR;
;     __device__ __forceinline__ void operator()(const f32x4 (&acc)[2][2][4][2], const pg8::Unit& u, int wr, int wc, int fr, int fq) const {
;         const int row0 = u.pm * 256 + wr * 64 + fr, col0 = u.pn * 128 + wc * 32 + 8 * fq;
; #pragma unroll
;         for (int ai = 0; ai < 2; ++ai)
; #pragma unroll
;             for (int m = 0; m < 4; ++m) { bf16_t* rowp = O + (size_t)(row0 + ai * 128 + m * 16) * ldc + col0;
;                 const f32x4 g0 = acc[ai][0][m][0], g1 = acc[ai][0][m][1], u0 = acc[ai][1][m][0], u1 = acc[ai][1][m][1];
;                 u32x4 w; w.x = cvtpk(siluf_(g0[0]) * u0[0], siluf_(g0[1]) * u0[1]); w.y = cvtpk(siluf_(g0[2]) * u0[2], siluf_(g0[3]) * u0[3]);
;                 w.z = cvtpk(siluf_(g1[0]) * u1[0], siluf_(g1[1]) * u1[1]); w.w = cvtpk(siluf_(g1[2]) * u1[2], siluf_(g1[3]) * u1[3]);
;                 *(u32x4*)rowp = w; }
;     }
	s_waitcnt lgkmcnt(0)
	s_setprio 1
	v_mfma_f32_16x16x32_bf16 v[60:63], v[138:141], v[158:161], v[60:63]
	v_mfma_f32_16x16x32_bf16 v[52:55], v[150:153], v[158:161], v[52:55]
	v_mfma_f32_16x16x32_bf16 v[44:47], v[138:141], v[166:169], v[44:47]
	v_mfma_f32_16x16x32_bf16 v[36:39], v[150:153], v[166:169], v[36:39]
	v_mfma_f32_16x16x32_bf16 v[28:31], v[138:141], v[178:181], v[28:31]
	v_mfma_f32_16x16x32_bf16 v[20:23], v[150:153], v[178:181], v[20:23]
	v_mfma_f32_16x16x32_bf16 v[12:15], v[138:141], v[186:189], v[12:15]
	v_mfma_f32_16x16x32_bf16 v[4:7], v[150:153], v[186:189], v[4:7]
	v_mfma_f32_16x16x32_bf16 v[60:63], v[146:149], v[162:165], v[60:63]
	v_mfma_f32_16x16x32_bf16 v[52:55], v[154:157], v[162:165], v[52:55]
	v_mfma_f32_16x16x32_bf16 v[44:47], v[146:149], v[170:173], v[44:47]
	v_mfma_f32_16x16x32_bf16 v[36:39], v[154:157], v[170:173], v[36:39]
	v_mfma_f32_16x16x32_bf16 v[28:31], v[146:149], v[182:185], v[28:31]
	v_mfma_f32_16x16x32_bf16 v[20:23], v[154:157], v[182:185], v[20:23]
	v_mfma_f32_16x16x32_bf16 v[12:15], v[146:149], v[190:193], v[12:15]
	v_mfma_f32_16x16x32_bf16 v[4:7], v[154:157], v[190:193], v[4:7]
	s_setprio 0
	s_barrier
	s_add_u32 s14, s14, 0x40080
	s_addc_u32 s15, s15, 0
	s_add_i32 s16, s16, s20
	v_lshl_add_u64 v[138:139], s[14:15], 0, v[176:177]
	s_mov_b32 m0, s16
	s_nop 0
	global_load_lds_dwordx4 v[138:139], off
	v_lshl_add_u64 v[138:139], s[14:15], 0, v[128:129]
	s_add_i32 m0, s16, 0x2000
	s_nop 0
	global_load_lds_dwordx4 v[138:139], off
	s_waitcnt vmcnt(6)
	s_barrier
	s_setprio 1
	v_mfma_f32_16x16x32_bf16 v[56:59], v[194:197], v[158:161], v[56:59]
	v_mfma_f32_16x16x32_bf16 v[48:51], v[202:205], v[158:161], v[48:51]
	v_mfma_f32_16x16x32_bf16 v[40:43], v[194:197], v[166:169], v[40:43]
	v_mfma_f32_16x16x32_bf16 v[32:35], v[202:205], v[166:169], v[32:35]
	v_mfma_f32_16x16x32_bf16 v[24:27], v[194:197], v[178:181], v[24:27]
	v_mfma_f32_16x16x32_bf16 v[16:19], v[202:205], v[178:181], v[16:19]
	v_mfma_f32_16x16x32_bf16 v[8:11], v[194:197], v[186:189], v[8:11]
	v_mfma_f32_16x16x32_bf16 v[0:3], v[202:205], v[186:189], v[0:3]
	v_mfma_f32_16x16x32_bf16 v[56:59], v[198:201], v[162:165], v[56:59]
	v_mfma_f32_16x16x32_bf16 v[48:51], v[206:209], v[162:165], v[48:51]
	v_mfma_f32_16x16x32_bf16 v[40:43], v[198:201], v[170:173], v[40:43]
	v_mfma_f32_16x16x32_bf16 v[32:35], v[206:209], v[170:173], v[32:35]
	v_mfma_f32_16x16x32_bf16 v[24:27], v[198:201], v[182:185], v[24:27]
	v_mfma_f32_16x16x32_bf16 v[16:19], v[206:209], v[182:185], v[16:19]
	v_mfma_f32_16x16x32_bf16 v[8:11], v[198:201], v[190:193], v[8:11]
	v_mfma_f32_16x16x32_bf16 v[0:3], v[206:209], v[190:193], v[0:3]
	s_setprio 0
	s_add_i32 s45, s45, 2
	s_add_u32 s12, s12, 0x100
	s_addc_u32 s13, s13, 0
	s_add_u32 s43, s43, 0x100
	s_addc_u32 s44, s44, 0
	s_cmp_gt_u32 s45, 13
	s_barrier
	s_cbranch_scc0 .LBB0_114
	v_mul_f32_e32 v147, 0xbfb8aa3b, v124
	v_exp_f32_e32 v147, v147
	v_readlane_b32 s12, v253, 16
	v_lshl_add_u32 v146, s10, 8, v142
	v_lshl_or_b32 v140, s34, 7, v144
	v_add_f32_e32 v147, 1.0, v147
	v_rcp_f32_e32 v150, v147
	v_mul_f32_e32 v147, 0xbfb8aa3b, v125
	v_exp_f32_e32 v147, v147
	v_readlane_b32 s13, v253, 17
	v_ashrrev_i32_e32 v141, 31, v140
	v_lshlrev_b64 v[140:141], 1, v[140:141]
	v_add_f32_e32 v147, 1.0, v147
	v_rcp_f32_e32 v151, v147
	v_mov_b64_e32 v[138:139], s[12:13]
	v_mad_i64_i32 v[148:149], s[12:13], v146, s81, v[138:139]
	v_pk_mul_f32 v[124:125], v[124:125], v[150:151]
	v_lshl_add_u64 v[148:149], v[148:149], 0, v[140:141]
	v_pk_mul_f32 v[120:121], v[124:125], v[120:121]
	s_and_b64 vcc, exec, s[38:39]
	v_cvt_pk_bf16_f32 v120, v120, v121
	v_mul_f32_e32 v121, 0xbfb8aa3b, v126
	v_exp_f32_e32 v121, v121
	s_mov_b32 s34, s0
	s_mov_b32 s10, s4
	s_mov_b64 s[14:15], s[8:9]
	v_add_f32_e32 v121, 1.0, v121
	v_rcp_f32_e32 v124, v121
	v_mul_f32_e32 v121, 0xbfb8aa3b, v127
	v_exp_f32_e32 v121, v121
	s_nop 0
	v_add_f32_e32 v121, 1.0, v121
	v_rcp_f32_e32 v125, v121
	s_nop 0
	v_pk_mul_f32 v[124:125], v[126:127], v[124:125]
	s_nop 0
	v_pk_mul_f32 v[122:123], v[124:125], v[122:123]
	s_nop 0
	v_cvt_pk_bf16_f32 v121, v122, v123
	v_mul_f32_e32 v122, 0xbfb8aa3b, v116
	v_mul_f32_e32 v123, 0xbfb8aa3b, v117
	v_exp_f32_e32 v122, v122
	v_exp_f32_e32 v123, v123
	v_add_f32_e32 v122, 1.0, v122
	v_add_f32_e32 v123, 1.0, v123
	v_rcp_f32_e32 v122, v122
	v_rcp_f32_e32 v123, v123
	s_nop 0
	v_pk_mul_f32 v[116:117], v[116:117], v[122:123]
	s_nop 0
	v_pk_mul_f32 v[112:113], v[116:117], v[112:113]
	s_nop 0
	v_cvt_pk_bf16_f32 v122, v112, v113
	v_mul_f32_e32 v112, 0xbfb8aa3b, v118
	v_mul_f32_e32 v113, 0xbfb8aa3b, v119
	v_exp_f32_e32 v112, v112
	v_exp_f32_e32 v113, v113
	v_add_f32_e32 v112, 1.0, v112
	v_add_f32_e32 v113, 1.0, v113
	v_rcp_f32_e32 v112, v112
	v_rcp_f32_e32 v113, v113
	s_nop 0
	v_pk_mul_f32 v[112:113], v[118:119], v[112:113]
	s_nop 0
	v_pk_mul_f32 v[112:113], v[112:113], v[114:115]
	v_mul_f32_e32 v114, 0xbfb8aa3b, v108
	v_mul_f32_e32 v115, 0xbfb8aa3b, v109
	v_exp_f32_e32 v114, v114
	v_exp_f32_e32 v115, v115
	v_cvt_pk_bf16_f32 v123, v112, v113
	v_or_b32_e32 v112, 16, v146
	v_add_f32_e32 v114, 1.0, v114
	v_add_f32_e32 v115, 1.0, v115
	v_rcp_f32_e32 v114, v114
	v_rcp_f32_e32 v115, v115
	v_mad_i64_i32 v[112:113], s[12:13], v112, s81, v[138:139]
	v_lshl_add_u64 v[112:113], v[112:113], 0, v[140:141]
	v_pk_mul_f32 v[108:109], v[108:109], v[114:115]
	global_store_dwordx4 v[148:149], v[120:123], off
	v_pk_mul_f32 v[104:105], v[108:109], v[104:105]
	s_nop 0
	v_cvt_pk_bf16_f32 v104, v104, v105
	v_mul_f32_e32 v105, 0xbfb8aa3b, v110
	v_exp_f32_e32 v105, v105
	s_nop 0
	v_add_f32_e32 v105, 1.0, v105
	v_rcp_f32_e32 v108, v105
	v_mul_f32_e32 v105, 0xbfb8aa3b, v111
	v_exp_f32_e32 v105, v105
	s_nop 0
; __device__ __forceinline__ unsigned cvtpk(float lo, float hi) { const f32x2 v = (f32x2){lo, hi}; const bf16v2 b = __builtin_convertvector(v, bf16v2); return __builtin_bit_cast(unsigned, b); }
; __device__ __forceinline__ float siluf_(float x) { return x * sigmoidf_(x); }
;     __device__ __forceinline__ void operator()(const f32x4 (&acc)[2][2][4][2], const pg8::Unit& u, int wr, int wc, int fr, int fq) const {
;         const int row0 = u.pm * 256 + wr * 64 + fr, col0 = u.pn * 128 + wc * 32 + 8 * fq;
; #pragma unroll
;         for (int ai = 0; ai < 2; ++ai)
; #pragma unroll
;             for (int m = 0; m < 4; ++m) { bf16_t* rowp = O + (size_t)(row0 + ai * 128 + m * 16) * ldc + col0;
;                 const f32x4 g0 = acc[ai][0][m][0], g1 = acc[ai][0][m][1], u0 = acc[ai][1][m][0], u1 = acc[ai][1][m][1];
;                 u32x4 w; w.x = cvtpk(siluf_(g0[0]) * u0[0], siluf_(g0[1]) * u0[1]); w.y = cvtpk(siluf_(g0[2]) * u0[2], siluf_(g0[3]) * u0[3]);
;                 w.z = cvtpk(siluf_(g1[0]) * u1[0], siluf_(g1[1]) * u1[1]); w.w = cvtpk(siluf_(g1[2]) * u1[2], siluf_(g1[3]) * u1[3]);
;                 *(u32x4*)rowp = w; }
;     }
	v_add_f32_e32 v105, 1.0, v105
	v_rcp_f32_e32 v109, v105
	s_nop 0
	v_pk_mul_f32 v[108:109], v[110:111], v[108:109]
	s_nop 0
	v_pk_mul_f32 v[106:107], v[108:109], v[106:107]
	s_nop 0
	v_cvt_pk_bf16_f32 v105, v106, v107
	v_mul_f32_e32 v106, 0xbfb8aa3b, v100
	v_mul_f32_e32 v107, 0xbfb8aa3b, v101
	v_exp_f32_e32 v106, v106
	v_exp_f32_e32 v107, v107
	v_add_f32_e32 v106, 1.0, v106
	v_add_f32_e32 v107, 1.0, v107
	v_rcp_f32_e32 v106, v106
	v_rcp_f32_e32 v107, v107
	s_nop 0
	v_pk_mul_f32 v[100:101], v[100:101], v[106:107]
	s_nop 0
	v_pk_mul_f32 v[96:97], v[100:101], v[96:97]
	s_nop 0
	v_cvt_pk_bf16_f32 v106, v96, v97
	v_mul_f32_e32 v96, 0xbfb8aa3b, v102
	v_mul_f32_e32 v97, 0xbfb8aa3b, v103
	v_exp_f32_e32 v96, v96
	v_exp_f32_e32 v97, v97
	v_add_f32_e32 v96, 1.0, v96
	v_add_f32_e32 v97, 1.0, v97
	v_rcp_f32_e32 v96, v96
	v_rcp_f32_e32 v97, v97
	s_nop 0
	v_pk_mul_f32 v[96:97], v[102:103], v[96:97]
	s_nop 0
	v_pk_mul_f32 v[96:97], v[96:97], v[98:99]
	v_mul_f32_e32 v98, 0xbfb8aa3b, v92
	v_mul_f32_e32 v99, 0xbfb8aa3b, v93
	v_exp_f32_e32 v98, v98
	v_exp_f32_e32 v99, v99
	v_cvt_pk_bf16_f32 v107, v96, v97
	v_or_b32_e32 v96, 32, v146
	v_add_f32_e32 v98, 1.0, v98
	v_add_f32_e32 v99, 1.0, v99
	v_rcp_f32_e32 v98, v98
	v_rcp_f32_e32 v99, v99
	v_mad_i64_i32 v[96:97], s[12:13], v96, s81, v[138:139]
	v_lshl_add_u64 v[96:97], v[96:97], 0, v[140:141]
	v_pk_mul_f32 v[92:93], v[92:93], v[98:99]
	global_store_dwordx4 v[112:113], v[104:107], off
	v_pk_mul_f32 v[88:89], v[92:93], v[88:89]
	s_nop 0
	v_cvt_pk_bf16_f32 v88, v88, v89
	v_mul_f32_e32 v89, 0xbfb8aa3b, v94
	v_exp_f32_e32 v89, v89
	s_nop 0
	v_add_f32_e32 v89, 1.0, v89
	v_rcp_f32_e32 v92, v89
	v_mul_f32_e32 v89, 0xbfb8aa3b, v95
	v_exp_f32_e32 v89, v89
	s_nop 0
	v_add_f32_e32 v89, 1.0, v89
	v_rcp_f32_e32 v93, v89
	s_nop 0
	v_pk_mul_f32 v[92:93], v[94:95], v[92:93]
	s_nop 0
	v_pk_mul_f32 v[90:91], v[92:93], v[90:91]
	s_nop 0
	v_cvt_pk_bf16_f32 v89, v90, v91
	v_mul_f32_e32 v90, 0xbfb8aa3b, v84
	v_mul_f32_e32 v91, 0xbfb8aa3b, v85
	v_exp_f32_e32 v90, v90
	v_exp_f32_e32 v91, v91
	v_add_f32_e32 v90, 1.0, v90
	v_add_f32_e32 v91, 1.0, v91
	v_rcp_f32_e32 v90, v90
	v_rcp_f32_e32 v91, v91
	s_nop 0
	v_pk_mul_f32 v[84:85], v[84:85], v[90:91]
	s_nop 0
	v_pk_mul_f32 v[80:81], v[84:85], v[80:81]
	s_nop 0
	v_cvt_pk_bf16_f32 v90, v80, v81
	v_mul_f32_e32 v80, 0xbfb8aa3b, v86
	v_mul_f32_e32 v81, 0xbfb8aa3b, v87
	v_exp_f32_e32 v80, v80
	v_exp_f32_e32 v81, v81
	v_add_f32_e32 v80, 1.0, v80
	v_add_f32_e32 v81, 1.0, v81
	v_rcp_f32_e32 v80, v80
	v_rcp_f32_e32 v81, v81
	s_nop 0
	v_pk_mul_f32 v[80:81], v[86:87], v[80:81]
	s_nop 0
	v_pk_mul_f32 v[80:81], v[80:81], v[82:83]
	v_mul_f32_e32 v82, 0xbfb8aa3b, v76
	v_mul_f32_e32 v83, 0xbfb8aa3b, v77
	v_exp_f32_e32 v82, v82
	v_exp_f32_e32 v83, v83
	v_cvt_pk_bf16_f32 v91, v80, v81
	v_or_b32_e32 v80, 48, v146
	v_add_f32_e32 v82, 1.0, v82
	v_add_f32_e32 v83, 1.0, v83
	v_rcp_f32_e32 v82, v82
	v_rcp_f32_e32 v83, v83
	v_mad_i64_i32 v[80:81], s[12:13], v80, s81, v[138:139]
	v_lshl_add_u64 v[80:81], v[80:81], 0, v[140:141]
	v_pk_mul_f32 v[76:77], v[76:77], v[82:83]
	global_store_dwordx4 v[96:97], v[88:91], off
	v_pk_mul_f32 v[72:73], v[76:77], v[72:73]
	s_nop 0
	v_cvt_pk_bf16_f32 v72, v72, v73
	v_mul_f32_e32 v73, 0xbfb8aa3b, v78
	v_exp_f32_e32 v73, v73
	s_nop 0
	v_add_f32_e32 v73, 1.0, v73
	v_rcp_f32_e32 v76, v73
	v_mul_f32_e32 v73, 0xbfb8aa3b, v79
	v_exp_f32_e32 v73, v73
	s_nop 0
	v_add_f32_e32 v73, 1.0, v73
	v_rcp_f32_e32 v77, v73
	s_nop 0
	v_pk_mul_f32 v[76:77], v[78:79], v[76:77]
	s_nop 0
	v_pk_mul_f32 v[74:75], v[76:77], v[74:75]
	s_nop 0
	v_cvt_pk_bf16_f32 v73, v74, v75
	v_mul_f32_e32 v74, 0xbfb8aa3b, v68
	v_mul_f32_e32 v75, 0xbfb8aa3b, v69
	v_exp_f32_e32 v74, v74
	v_exp_f32_e32 v75, v75
	v_add_f32_e32 v74, 1.0, v74
	v_add_f32_e32 v75, 1.0, v75
	v_rcp_f32_e32 v74, v74
	v_rcp_f32_e32 v75, v75
	s_nop 0
	v_pk_mul_f32 v[68:69], v[68:69], v[74:75]
	s_nop 0
	v_pk_mul_f32 v[64:65], v[68:69], v[64:65]
	s_nop 0
	v_cvt_pk_bf16_f32 v74, v64, v65
	v_mul_f32_e32 v64, 0xbfb8aa3b, v70
	v_mul_f32_e32 v65, 0xbfb8aa3b, v71
	v_exp_f32_e32 v64, v64
	v_exp_f32_e32 v65, v65
	v_add_f32_e32 v64, 1.0, v64
	v_add_f32_e32 v65, 1.0, v65
	v_rcp_f32_e32 v64, v64
	v_rcp_f32_e32 v65, v65
	s_nop 0
	v_pk_mul_f32 v[64:65], v[70:71], v[64:65]
	s_nop 0
	v_pk_mul_f32 v[64:65], v[64:65], v[66:67]
	v_mul_f32_e32 v66, 0xbfb8aa3b, v60
	v_mul_f32_e32 v67, 0xbfb8aa3b, v61
	v_exp_f32_e32 v66, v66
	v_exp_f32_e32 v67, v67
	v_cvt_pk_bf16_f32 v75, v64, v65
	v_add_u32_e32 v64, 0x80, v146
	v_add_f32_e32 v66, 1.0, v66
	v_add_f32_e32 v67, 1.0, v67
	v_rcp_f32_e32 v66, v66
	v_rcp_f32_e32 v67, v67
	v_mad_i64_i32 v[64:65], s[12:13], v64, s81, v[138:139]
	v_lshl_add_u64 v[64:65], v[64:65], 0, v[140:141]
	v_pk_mul_f32 v[60:61], v[60:61], v[66:67]
	global_store_dwordx4 v[80:81], v[72:75], off
	v_pk_mul_f32 v[56:57], v[60:61], v[56:57]
	s_nop 0
	v_cvt_pk_bf16_f32 v56, v56, v57
	v_mul_f32_e32 v57, 0xbfb8aa3b, v62
	v_exp_f32_e32 v57, v57
	s_nop 0
	v_add_f32_e32 v57, 1.0, v57
	v_rcp_f32_e32 v60, v57
	v_mul_f32_e32 v57, 0xbfb8aa3b, v63
	v_exp_f32_e32 v57, v57
	s_nop 0
	v_add_f32_e32 v57, 1.0, v57
	v_rcp_f32_e32 v61, v57
	s_nop 0
	v_pk_mul_f32 v[60:61], v[62:63], v[60:61]
	s_nop 0
	v_pk_mul_f32 v[58:59], v[60:61], v[58:59]
	s_nop 0
	v_cvt_pk_bf16_f32 v57, v58, v59
	v_mul_f32_e32 v58, 0xbfb8aa3b, v52
	v_mul_f32_e32 v59, 0xbfb8aa3b, v53
	v_exp_f32_e32 v58, v58
	v_exp_f32_e32 v59, v59
	v_add_f32_e32 v58, 1.0, v58
	v_add_f32_e32 v59, 1.0, v59
	v_rcp_f32_e32 v58, v58
	v_rcp_f32_e32 v59, v59
	s_nop 0
	v_pk_mul_f32 v[52:53], v[52:53], v[58:59]
	s_nop 0
	v_pk_mul_f32 v[48:49], v[52:53], v[48:49]
	s_nop 0
; __device__ __forceinline__ unsigned cvtpk(float lo, float hi) { const f32x2 v = (f32x2){lo, hi}; const bf16v2 b = __builtin_convertvector(v, bf16v2); return __builtin_bit_cast(unsigned, b); }
; __device__ __forceinline__ float siluf_(float x) { return x * sigmoidf_(x); }
; #define PG8_WAIT_V(n) asm volatile("s_waitcnt vmcnt(" #n ")" ::: "memory")
; #define PG8_BAR __builtin_amdgcn_s_barrier()
; template <class Epi, class Sched>
; __device__ __forceinline__ void gemm_phase(PG8_LAS unsigned char* lds, const Gemm g, const Sched& S, const Epi& E) {
;     ...
;         if constexpr (!Epi::AFTER_DRAIN) { E(acc, cur, wr, wc, fr, fq); S.done(cur); }
;         if (!has_next) break;
; #pragma unroll
;         for (int a = 0; a < 2; ++a)
; #pragma unroll
;             for (int b = 0; b < 2; ++b)
; #pragma unroll
;                 for (int m = 0; m < 4; ++m)
; #pragma unroll
;                     for (int n = 0; n < 2; ++n) acc[a][b][m][n] = (f32x4){0.f, 0.f, 0.f, 0.f};
;         cur = nxt; cA = nA; cB = nB; ++ui;
;     }
;     PG8_WAIT_V(0);
;     if (wr == 0) PG8_BAR;
;     __device__ __forceinline__ void operator()(const f32x4 (&acc)[2][2][4][2], const pg8::Unit& u, int wr, int wc, int fr, int fq) const {
;         const int row0 = u.pm * 256 + wr * 64 + fr, col0 = u.pn * 128 + wc * 32 + 8 * fq;
; #pragma unroll
;         for (int ai = 0; ai < 2; ++ai)
; #pragma unroll
;             for (int m = 0; m < 4; ++m) { bf16_t* rowp = O + (size_t)(row0 + ai * 128 + m * 16) * ldc + col0;
;                 const f32x4 g0 = acc[ai][0][m][0], g1 = acc[ai][0][m][1], u0 = acc[ai][1][m][0], u1 = acc[ai][1][m][1];
;                 u32x4 w; w.x = cvtpk(siluf_(g0[0]) * u0[0], siluf_(g0[1]) * u0[1]); w.y = cvtpk(siluf_(g0[2]) * u0[2], siluf_(g0[3]) * u0[3]);
;                 w.z = cvtpk(siluf_(g1[0]) * u1[0], siluf_(g1[1]) * u1[1]); w.w = cvtpk(siluf_(g1[2]) * u1[2], siluf_(g1[3]) * u1[3]);
;                 *(u32x4*)rowp = w; }
;     }
	v_cvt_pk_bf16_f32 v58, v48, v49
	v_mul_f32_e32 v48, 0xbfb8aa3b, v54
	v_mul_f32_e32 v49, 0xbfb8aa3b, v55
	v_exp_f32_e32 v48, v48
	v_exp_f32_e32 v49, v49
	v_add_f32_e32 v48, 1.0, v48
	v_add_f32_e32 v49, 1.0, v49
	v_rcp_f32_e32 v48, v48
	v_rcp_f32_e32 v49, v49
	s_nop 0
	v_pk_mul_f32 v[48:49], v[54:55], v[48:49]
	s_nop 0
	v_pk_mul_f32 v[48:49], v[48:49], v[50:51]
	v_mul_f32_e32 v50, 0xbfb8aa3b, v44
	v_mul_f32_e32 v51, 0xbfb8aa3b, v45
	v_exp_f32_e32 v50, v50
	v_exp_f32_e32 v51, v51
	v_cvt_pk_bf16_f32 v59, v48, v49
	v_add_u32_e32 v48, 0x90, v146
	v_add_f32_e32 v50, 1.0, v50
	v_add_f32_e32 v51, 1.0, v51
	v_rcp_f32_e32 v50, v50
	v_rcp_f32_e32 v51, v51
	v_mad_i64_i32 v[48:49], s[12:13], v48, s81, v[138:139]
	v_lshl_add_u64 v[48:49], v[48:49], 0, v[140:141]
	v_pk_mul_f32 v[44:45], v[44:45], v[50:51]
	global_store_dwordx4 v[64:65], v[56:59], off
	v_pk_mul_f32 v[40:41], v[44:45], v[40:41]
	s_nop 0
	v_cvt_pk_bf16_f32 v40, v40, v41
	v_mul_f32_e32 v41, 0xbfb8aa3b, v46
	v_exp_f32_e32 v41, v41
	s_nop 0
	v_add_f32_e32 v41, 1.0, v41
	v_rcp_f32_e32 v44, v41
	v_mul_f32_e32 v41, 0xbfb8aa3b, v47
	v_exp_f32_e32 v41, v41
	s_nop 0
	v_add_f32_e32 v41, 1.0, v41
	v_rcp_f32_e32 v45, v41
	s_nop 0
	v_pk_mul_f32 v[44:45], v[46:47], v[44:45]
	s_nop 0
	v_pk_mul_f32 v[42:43], v[44:45], v[42:43]
	s_nop 0
	v_cvt_pk_bf16_f32 v41, v42, v43
	v_mul_f32_e32 v42, 0xbfb8aa3b, v36
	v_mul_f32_e32 v43, 0xbfb8aa3b, v37
	v_exp_f32_e32 v42, v42
	v_exp_f32_e32 v43, v43
	v_add_f32_e32 v42, 1.0, v42
	v_add_f32_e32 v43, 1.0, v43
	v_rcp_f32_e32 v42, v42
	v_rcp_f32_e32 v43, v43
	s_nop 0
	v_pk_mul_f32 v[36:37], v[36:37], v[42:43]
	s_nop 0
	v_pk_mul_f32 v[32:33], v[36:37], v[32:33]
	s_nop 0
	v_cvt_pk_bf16_f32 v42, v32, v33
	v_mul_f32_e32 v32, 0xbfb8aa3b, v38
	v_mul_f32_e32 v33, 0xbfb8aa3b, v39
	v_exp_f32_e32 v32, v32
	v_exp_f32_e32 v33, v33
	v_add_f32_e32 v32, 1.0, v32
	v_add_f32_e32 v33, 1.0, v33
	v_rcp_f32_e32 v32, v32
	v_rcp_f32_e32 v33, v33
	s_nop 0
	v_pk_mul_f32 v[32:33], v[38:39], v[32:33]
	s_nop 0
	v_pk_mul_f32 v[32:33], v[32:33], v[34:35]
	v_mul_f32_e32 v34, 0xbfb8aa3b, v28
	v_mul_f32_e32 v35, 0xbfb8aa3b, v29
	v_exp_f32_e32 v34, v34
	v_exp_f32_e32 v35, v35
	v_cvt_pk_bf16_f32 v43, v32, v33
	v_add_u32_e32 v32, 0xa0, v146
	v_add_f32_e32 v34, 1.0, v34
	v_add_f32_e32 v35, 1.0, v35
	v_rcp_f32_e32 v34, v34
	v_rcp_f32_e32 v35, v35
	v_mad_i64_i32 v[32:33], s[12:13], v32, s81, v[138:139]
	v_lshl_add_u64 v[32:33], v[32:33], 0, v[140:141]
	v_pk_mul_f32 v[28:29], v[28:29], v[34:35]
	global_store_dwordx4 v[48:49], v[40:43], off
	v_pk_mul_f32 v[24:25], v[28:29], v[24:25]
	s_nop 0
	v_cvt_pk_bf16_f32 v24, v24, v25
	v_mul_f32_e32 v25, 0xbfb8aa3b, v30
	v_exp_f32_e32 v25, v25
	s_nop 0
	v_add_f32_e32 v25, 1.0, v25
	v_rcp_f32_e32 v28, v25
	v_mul_f32_e32 v25, 0xbfb8aa3b, v31
	v_exp_f32_e32 v25, v25
	s_nop 0
	v_add_f32_e32 v25, 1.0, v25
	v_rcp_f32_e32 v29, v25
	s_nop 0
	v_pk_mul_f32 v[28:29], v[30:31], v[28:29]
	s_nop 0
	v_pk_mul_f32 v[26:27], v[28:29], v[26:27]
	s_nop 0
	v_cvt_pk_bf16_f32 v25, v26, v27
	v_mul_f32_e32 v26, 0xbfb8aa3b, v20
	v_mul_f32_e32 v27, 0xbfb8aa3b, v21
	v_exp_f32_e32 v26, v26
	v_exp_f32_e32 v27, v27
	v_add_f32_e32 v26, 1.0, v26
	v_add_f32_e32 v27, 1.0, v27
	v_rcp_f32_e32 v26, v26
	v_rcp_f32_e32 v27, v27
	s_nop 0
	v_pk_mul_f32 v[20:21], v[20:21], v[26:27]
	s_nop 0
	v_pk_mul_f32 v[16:17], v[20:21], v[16:17]
	s_nop 0
	v_cvt_pk_bf16_f32 v26, v16, v17
	v_mul_f32_e32 v16, 0xbfb8aa3b, v22
	v_mul_f32_e32 v17, 0xbfb8aa3b, v23
	v_exp_f32_e32 v16, v16
	v_exp_f32_e32 v17, v17
	v_add_f32_e32 v16, 1.0, v16
	v_add_f32_e32 v17, 1.0, v17
	v_rcp_f32_e32 v16, v16
	v_rcp_f32_e32 v17, v17
	s_nop 0
	v_pk_mul_f32 v[16:17], v[22:23], v[16:17]
	s_nop 0
	v_pk_mul_f32 v[16:17], v[16:17], v[18:19]
	v_mul_f32_e32 v18, 0xbfb8aa3b, v12
	v_mul_f32_e32 v19, 0xbfb8aa3b, v13
	v_exp_f32_e32 v18, v18
	v_exp_f32_e32 v19, v19
	v_cvt_pk_bf16_f32 v27, v16, v17
	v_add_u32_e32 v16, 0xb0, v146
	v_add_f32_e32 v18, 1.0, v18
	v_add_f32_e32 v19, 1.0, v19
	v_rcp_f32_e32 v18, v18
	v_rcp_f32_e32 v19, v19
	v_mad_i64_i32 v[16:17], s[12:13], v16, s81, v[138:139]
	v_lshl_add_u64 v[16:17], v[16:17], 0, v[140:141]
	v_pk_mul_f32 v[12:13], v[12:13], v[18:19]
	s_mov_b64 s[12:13], s[6:7]
	v_pk_mul_f32 v[8:9], v[12:13], v[8:9]
	global_store_dwordx4 v[32:33], v[24:27], off
	v_cvt_pk_bf16_f32 v8, v8, v9
	v_mul_f32_e32 v9, 0xbfb8aa3b, v14
	v_exp_f32_e32 v9, v9
	s_nop 0
	v_add_f32_e32 v9, 1.0, v9
	v_rcp_f32_e32 v12, v9
	v_mul_f32_e32 v9, 0xbfb8aa3b, v15
	v_exp_f32_e32 v9, v9
	s_nop 0
	v_add_f32_e32 v9, 1.0, v9
	v_rcp_f32_e32 v13, v9
	s_nop 0
	v_pk_mul_f32 v[12:13], v[14:15], v[12:13]
	s_nop 0
	v_pk_mul_f32 v[10:11], v[12:13], v[10:11]
	s_nop 0
	v_cvt_pk_bf16_f32 v9, v10, v11
	v_mul_f32_e32 v10, 0xbfb8aa3b, v4
	v_mul_f32_e32 v11, 0xbfb8aa3b, v5
	v_exp_f32_e32 v10, v10
	v_exp_f32_e32 v11, v11
	v_add_f32_e32 v10, 1.0, v10
	v_add_f32_e32 v11, 1.0, v11
	v_rcp_f32_e32 v10, v10
	v_rcp_f32_e32 v11, v11
	s_nop 0
	v_pk_mul_f32 v[4:5], v[4:5], v[10:11]
	s_nop 0
	v_pk_mul_f32 v[0:1], v[4:5], v[0:1]
	s_nop 0
	v_cvt_pk_bf16_f32 v10, v0, v1
	v_mul_f32_e32 v0, 0xbfb8aa3b, v6
	v_mul_f32_e32 v1, 0xbfb8aa3b, v7
	v_exp_f32_e32 v0, v0
	v_exp_f32_e32 v1, v1
	v_add_f32_e32 v0, 1.0, v0
	v_add_f32_e32 v1, 1.0, v1
	v_rcp_f32_e32 v0, v0
	v_rcp_f32_e32 v1, v1
	s_nop 0
	v_pk_mul_f32 v[0:1], v[6:7], v[0:1]
	s_nop 0
	v_pk_mul_f32 v[0:1], v[0:1], v[2:3]
	s_nop 0
	v_cvt_pk_bf16_f32 v11, v0, v1
	global_store_dwordx4 v[16:17], v[8:11], off
	s_cbranch_vccz .LBB0_111
	s_waitcnt vmcnt(0)
	v_readlane_b32 s22, v255, 14
	s_cmpk_gt_u32 s19, 0xff
	v_readlane_b32 s23, v255, 15
	s_mov_b64 s[28:29], s[54:55]
	s_cbranch_scc1 .LBB0_118
	s_barrier

; #define PG8_STAGE(bufoff, gbase, voff) do { _Pragma("unroll") for (int _i = 0; _i < 2; ++_i) \
;         __builtin_amdgcn_global_load_lds((const unsigned*)((const char*)(gbase) + (voff)[_i]), (PG8_LAS unsigned*)(lds + (bufoff) + ldsw + _i * 8192), 16, 0, 0); } while (0)
; #define PG8_LDA(dst, b, h) do { _Pragma("unroll") for (int m = 0; m < 4; ++m) _Pragma("unroll") for (int k = 0; k < 2; ++k) dst[m][k] = *(const PG8_LAS bf16x8*)(lds + PG8_SA(b, h) + aoff + m * 2048 + k * 1024); } while (0)
; #define PG8_LDB(dst, b, h) do { _Pragma("unroll") for (int n = 0; n < 2; ++n) _Pragma("unroll") for (int k = 0; k < 2; ++k) dst[n][k] = *(const PG8_LAS bf16x8*)(lds + PG8_SB(b, h) + boff + n * 2048 + k * 1024); } while (0)
; #define PG8_MMA(ai, bj, At, Bt) do { __builtin_amdgcn_s_setprio(1); _Pragma("unroll") for (int m = 0; m < 4; ++m) _Pragma("unroll") for (int n = 0; n < 2; ++n) _Pragma("unroll") for (int k = 0; k < 2; ++k) \
;         acc[ai][bj][m][n] = __builtin_amdgcn_mfma_f32_16x16x32_bf16(Bt[n][k], At[m][k], acc[ai][bj][m][n], 0, 0, 0); __builtin_amdgcn_s_setprio(0); } while (0)
; #define PG8_WAIT_L(n) asm volatile("s_waitcnt lgkmcnt(" #n ")" ::: "memory")
; #define PG8_BAR __builtin_amdgcn_s_barrier()
; #define PG8_SCHED __builtin_amdgcn_sched_barrier(0)
; template <class Epi, class Sched>
; __device__ __forceinline__ void gemm_phase(PG8_LAS unsigned char* lds, const Gemm g, const Sched& S, const Epi& E) {
;     ...
;         for (int t = 0; t < nt; t += 2) {
;             const bool last = (t == nt - 2);
;             const char* a1 = cA + (size_t)(t + 1) * kstep;
;             const char* a2 = last ? nA : cA + (size_t)(t + 2) * kstep; const char* b2 = last ? nB : cB + (size_t)(t + 2) * kstep;
;             const char* a3 = a2 + kstep; const char* b3 = b2 + kstep;
;             if (last && has_next) S.a_ready(nxt);
;             PG8_LDB(B0, 0, 0); PG8_SCHED; PG8_LDA(At, 0, 0); PG8_STAGE(PG8_SA(1, 1), a1 + hstep, voffA);
;             PG8_WAIT_L(8); PG8_BAR; PG8_WAIT_L(0); PG8_MMA(0, 0, At, B0); PG8_BAR; PG8_SCHED;
;             PG8_LDB(B1, 0, 1); PG8_STAGE(PG8_SB(0, 0), b2, voffB);
;             PG8_BAR; PG8_WAIT_L(0); PG8_MMA(0, 1, At, B1); PG8_BAR;
;             PG8_LDA(At, 0, 1); PG8_STAGE(PG8_SA(0, 0), a2, voffA);
;             PG8_BAR; PG8_WAIT_L(0); PG8_MMA(1, 0, At, B0); PG8_BAR; PG8_SCHED;
.LBB0_137:
	s_add_u32 s14, s12, 0xfffc0080
	s_addc_u32 s15, s13, -1
	s_add_i32 s46, 0, 0x10000
	v_add_u32_e32 v154, s46, v139
	ds_read_b128 v[142:145], v154
	ds_read_b128 v[146:149], v154 offset:1024
	ds_read_b128 v[150:153], v154 offset:2048
	ds_read_b128 v[154:157], v154 offset:3072
	s_cmp_eq_u32 s45, 12
	s_cselect_b32 s17, s7, s15
	s_cselect_b32 s16, s40, s14
	s_cselect_b32 s15, s5, s44
	s_cselect_b32 s14, s41, s43
	v_lshl_add_u64 v[174:175], s[12:13], 0, v[134:135]
	s_add_i32 m0, s1, 0xc000
	ds_read_b128 v[158:161], v141
	ds_read_b128 v[162:165], v141 offset:1024
	ds_read_b128 v[166:169], v141 offset:2048
	ds_read_b128 v[170:173], v141 offset:3072
	ds_read_b128 v[178:181], v141 offset:4096
	ds_read_b128 v[182:185], v141 offset:5120
	ds_read_b128 v[186:189], v141 offset:6144
	ds_read_b128 v[190:193], v141 offset:7168
	global_load_lds_dwordx4 v[174:175], off
	v_lshl_add_u64 v[174:175], s[12:13], 0, v[136:137]
	s_add_i32 m0, s1, 0xe000
	s_nop 0
	global_load_lds_dwordx4 v[174:175], off
	s_waitcnt lgkmcnt(8)
	s_barrier
	s_waitcnt lgkmcnt(0)
	s_setprio 1
	v_mfma_f32_16x16x32_bf16 v[124:127], v[142:145], v[158:161], v[124:127]
	v_mfma_f32_16x16x32_bf16 v[120:123], v[150:153], v[158:161], v[120:123]
	v_mfma_f32_16x16x32_bf16 v[116:119], v[142:145], v[166:169], v[116:119]
	v_mfma_f32_16x16x32_bf16 v[112:115], v[150:153], v[166:169], v[112:115]
	v_mfma_f32_16x16x32_bf16 v[100:103], v[142:145], v[178:181], v[100:103]
	v_mfma_f32_16x16x32_bf16 v[96:99], v[150:153], v[178:181], v[96:99]
	v_mfma_f32_16x16x32_bf16 v[84:87], v[142:145], v[186:189], v[84:87]
	v_mfma_f32_16x16x32_bf16 v[80:83], v[150:153], v[186:189], v[80:83]
	v_mfma_f32_16x16x32_bf16 v[124:127], v[146:149], v[162:165], v[124:127]
	v_mfma_f32_16x16x32_bf16 v[120:123], v[154:157], v[162:165], v[120:123]
	v_mfma_f32_16x16x32_bf16 v[116:119], v[146:149], v[170:173], v[116:119]
	v_mfma_f32_16x16x32_bf16 v[112:115], v[154:157], v[170:173], v[112:115]
	v_mfma_f32_16x16x32_bf16 v[100:103], v[146:149], v[182:185], v[100:103]
	v_mfma_f32_16x16x32_bf16 v[96:99], v[154:157], v[182:185], v[96:99]
	v_mfma_f32_16x16x32_bf16 v[84:87], v[146:149], v[190:193], v[84:87]
	v_mfma_f32_16x16x32_bf16 v[80:83], v[154:157], v[190:193], v[80:83]
	s_setprio 0
	s_barrier
	s_add_i32 s48, 0, 0x14000
	v_add_u32_e32 v174, s48, v139
	s_add_i32 s46, s46, s20
	ds_read_b128 v[194:197], v174
	ds_read_b128 v[198:201], v174 offset:1024
	ds_read_b128 v[202:205], v174 offset:2048
	ds_read_b128 v[206:209], v174 offset:3072
	v_lshl_add_u64 v[174:175], s[14:15], 0, v[176:177]
	s_mov_b32 m0, s46
	v_lshl_add_u64 v[210:211], s[14:15], 0, v[128:129]
	global_load_lds_dwordx4 v[174:175], off
	s_add_i32 m0, s46, 0x2000
	s_nop 0
	global_load_lds_dwordx4 v[210:211], off
	s_barrier
	s_waitcnt lgkmcnt(0)
	s_setprio 1
	v_mfma_f32_16x16x32_bf16 v[108:111], v[194:197], v[158:161], v[108:111]
	v_mfma_f32_16x16x32_bf16 v[104:107], v[202:205], v[158:161], v[104:107]
	v_mfma_f32_16x16x32_bf16 v[92:95], v[194:197], v[166:169], v[92:95]
	v_mfma_f32_16x16x32_bf16 v[88:91], v[202:205], v[166:169], v[88:91]
	v_mfma_f32_16x16x32_bf16 v[76:79], v[194:197], v[178:181], v[76:79]
	v_mfma_f32_16x16x32_bf16 v[72:75], v[202:205], v[178:181], v[72:75]
	v_mfma_f32_16x16x32_bf16 v[68:71], v[194:197], v[186:189], v[68:71]
	v_mfma_f32_16x16x32_bf16 v[64:67], v[202:205], v[186:189], v[64:67]
	v_mfma_f32_16x16x32_bf16 v[108:111], v[198:201], v[162:165], v[108:111]
	v_mfma_f32_16x16x32_bf16 v[104:107], v[206:209], v[162:165], v[104:107]
	v_mfma_f32_16x16x32_bf16 v[92:95], v[198:201], v[170:173], v[92:95]
	v_mfma_f32_16x16x32_bf16 v[88:91], v[206:209], v[170:173], v[88:91]
	v_mfma_f32_16x16x32_bf16 v[76:79], v[198:201], v[182:185], v[76:79]
	v_mfma_f32_16x16x32_bf16 v[72:75], v[206:209], v[182:185], v[72:75]
	v_mfma_f32_16x16x32_bf16 v[68:71], v[198:201], v[190:193], v[68:71]
	v_mfma_f32_16x16x32_bf16 v[64:67], v[206:209], v[190:193], v[64:67]
	s_setprio 0
	s_mov_b32 m0, s1
	v_lshl_add_u64 v[212:213], s[16:17], 0, v[132:133]
	s_barrier
	ds_read_b128 v[158:161], v141 offset:16384
	ds_read_b128 v[162:165], v141 offset:17408
	ds_read_b128 v[166:169], v141 offset:18432
	ds_read_b128 v[170:173], v141 offset:19456
	ds_read_b128 v[178:181], v141 offset:20480
	ds_read_b128 v[182:185], v141 offset:21504
	ds_read_b128 v[186:189], v141 offset:22528
	ds_read_b128 v[190:193], v141 offset:23552
	global_load_lds_dwordx4 v[212:213], off
	v_lshl_add_u64 v[214:215], s[16:17], 0, v[130:131]
	s_mov_b32 m0, s22
	s_nop 0
	global_load_lds_dwordx4 v[214:215], off
	s_barrier
	s_waitcnt lgkmcnt(0)
	s_setprio 1
	v_mfma_f32_16x16x32_bf16 v[60:63], v[142:145], v[158:161], v[60:63]
	v_mfma_f32_16x16x32_bf16 v[56:59], v[150:153], v[158:161], v[56:59]
	v_mfma_f32_16x16x32_bf16 v[52:55], v[142:145], v[166:169], v[52:55]
	v_mfma_f32_16x16x32_bf16 v[48:51], v[150:153], v[166:169], v[48:51]
	v_mfma_f32_16x16x32_bf16 v[36:39], v[142:145], v[178:181], v[36:39]
	v_mfma_f32_16x16x32_bf16 v[32:35], v[150:153], v[178:181], v[32:35]
	v_mfma_f32_16x16x32_bf16 v[20:23], v[142:145], v[186:189], v[20:23]
	v_mfma_f32_16x16x32_bf16 v[16:19], v[150:153], v[186:189], v[16:19]
	v_mfma_f32_16x16x32_bf16 v[60:63], v[146:149], v[162:165], v[60:63]
	v_mfma_f32_16x16x32_bf16 v[56:59], v[154:157], v[162:165], v[56:59]
	v_mfma_f32_16x16x32_bf16 v[52:55], v[146:149], v[170:173], v[52:55]
	v_mfma_f32_16x16x32_bf16 v[48:51], v[154:157], v[170:173], v[48:51]
	v_mfma_f32_16x16x32_bf16 v[36:39], v[146:149], v[182:185], v[36:39]
	v_mfma_f32_16x16x32_bf16 v[32:35], v[154:157], v[182:185], v[32:35]
	v_mfma_f32_16x16x32_bf16 v[20:23], v[146:149], v[190:193], v[20:23]
	v_mfma_f32_16x16x32_bf16 v[16:19], v[154:157], v[190:193], v[16:19]
	s_setprio 0
	s_barrier
; #define PG8_STAGE(bufoff, gbase, voff) do { _Pragma("unroll") for (int _i = 0; _i < 2; ++_i) \
;         __builtin_amdgcn_global_load_lds((const unsigned*)((const char*)(gbase) + (voff)[_i]), (PG8_LAS unsigned*)(lds + (bufoff) + ldsw + _i * 8192), 16, 0, 0); } while (0)
; #define PG8_LDA(dst, b, h) do { _Pragma("unroll") for (int m = 0; m < 4; ++m) _Pragma("unroll") for (int k = 0; k < 2; ++k) dst[m][k] = *(const PG8_LAS bf16x8*)(lds + PG8_SA(b, h) + aoff + m * 2048 + k * 1024); } while (0)
; #define PG8_LDB(dst, b, h) do { _Pragma("unroll") for (int n = 0; n < 2; ++n) _Pragma("unroll") for (int k = 0; k < 2; ++k) dst[n][k] = *(const PG8_LAS bf16x8*)(lds + PG8_SB(b, h) + boff + n * 2048 + k * 1024); } while (0)
; #define PG8_MMA(ai, bj, At, Bt) do { __builtin_amdgcn_s_setprio(1); _Pragma("unroll") for (int m = 0; m < 4; ++m) _Pragma("unroll") for (int n = 0; n < 2; ++n) _Pragma("unroll") for (int k = 0; k < 2; ++k) \
;         acc[ai][bj][m][n] = __builtin_amdgcn_mfma_f32_16x16x32_bf16(Bt[n][k], At[m][k], acc[ai][bj][m][n], 0, 0, 0); __builtin_amdgcn_s_setprio(0); } while (0)
; #define PG8_WAIT_V(n) asm volatile("s_waitcnt vmcnt(" #n ")" ::: "memory")
; #define PG8_WAIT_L(n) asm volatile("s_waitcnt lgkmcnt(" #n ")" ::: "memory")
; #define PG8_BAR __builtin_amdgcn_s_barrier()
; #define PG8_SCHED __builtin_amdgcn_sched_barrier(0)
; template <class Epi, class Sched>
; __device__ __forceinline__ void gemm_phase(PG8_LAS unsigned char* lds, const Gemm g, const Sched& S, const Epi& E) {
;     ...
;             PG8_STAGE(PG8_SB(0, 1), b2 + hstep, voffB);
;             PG8_WAIT_V(6); PG8_BAR; PG8_MMA(1, 1, At, B1); PG8_BAR;
;             PG8_LDB(B0, 1, 0); PG8_SCHED; PG8_LDA(At, 1, 0); PG8_STAGE(PG8_SA(0, 1), a2 + hstep, voffA);
;             PG8_WAIT_L(8); PG8_BAR; PG8_WAIT_L(0); PG8_MMA(0, 0, At, B0); PG8_BAR; PG8_SCHED;
;             PG8_LDB(B1, 1, 1); PG8_STAGE(PG8_SB(1, 0), b3, voffB);
;             PG8_BAR; PG8_WAIT_L(0); PG8_MMA(0, 1, At, B1); PG8_BAR;
;             PG8_LDA(At, 1, 1); PG8_STAGE(PG8_SA(1, 0), a3, voffA);
	s_add_u32 s46, s14, 0x40000
	s_addc_u32 s47, s15, 0
	s_add_i32 s48, s48, s20
	v_lshl_add_u64 v[142:143], s[46:47], 0, v[176:177]
	s_mov_b32 m0, s48
	s_nop 0
	global_load_lds_dwordx4 v[142:143], off
	v_lshl_add_u64 v[142:143], s[46:47], 0, v[128:129]
	s_add_i32 m0, s48, 0x2000
	s_nop 0
	global_load_lds_dwordx4 v[142:143], off
	s_waitcnt vmcnt(6)
	s_barrier
	s_setprio 1
	v_mfma_f32_16x16x32_bf16 v[44:47], v[194:197], v[158:161], v[44:47]
	v_mfma_f32_16x16x32_bf16 v[40:43], v[202:205], v[158:161], v[40:43]
	v_mfma_f32_16x16x32_bf16 v[28:31], v[194:197], v[166:169], v[28:31]
	v_mfma_f32_16x16x32_bf16 v[24:27], v[202:205], v[166:169], v[24:27]
	v_mfma_f32_16x16x32_bf16 v[12:15], v[194:197], v[178:181], v[12:15]
	v_mfma_f32_16x16x32_bf16 v[8:11], v[202:205], v[178:181], v[8:11]
	v_mfma_f32_16x16x32_bf16 v[4:7], v[194:197], v[186:189], v[4:7]
	v_mfma_f32_16x16x32_bf16 v[0:3], v[202:205], v[186:189], v[0:3]
	v_mfma_f32_16x16x32_bf16 v[44:47], v[198:201], v[162:165], v[44:47]
	v_mfma_f32_16x16x32_bf16 v[40:43], v[206:209], v[162:165], v[40:43]
	v_mfma_f32_16x16x32_bf16 v[28:31], v[198:201], v[170:173], v[28:31]
	v_mfma_f32_16x16x32_bf16 v[24:27], v[206:209], v[170:173], v[24:27]
	v_mfma_f32_16x16x32_bf16 v[12:15], v[198:201], v[182:185], v[12:15]
	v_mfma_f32_16x16x32_bf16 v[8:11], v[206:209], v[182:185], v[8:11]
	v_mfma_f32_16x16x32_bf16 v[4:7], v[198:201], v[190:193], v[4:7]
	v_mfma_f32_16x16x32_bf16 v[0:3], v[206:209], v[190:193], v[0:3]
	s_setprio 0
	s_add_i32 s46, 0, 0x18000
	v_add_u32_e32 v154, s46, v139
	s_barrier
	ds_read_b128 v[142:145], v154
	ds_read_b128 v[146:149], v154 offset:1024
	ds_read_b128 v[150:153], v154 offset:2048
	ds_read_b128 v[154:157], v154 offset:3072
	s_add_u32 s16, s16, 0x40000
	s_addc_u32 s17, s17, 0
	s_mov_b32 m0, s23
	v_lshl_add_u64 v[194:195], s[16:17], 0, v[132:133]
	ds_read_b128 v[158:161], v141 offset:32768
	ds_read_b128 v[162:165], v141 offset:33792
	ds_read_b128 v[166:169], v141 offset:34816
	ds_read_b128 v[170:173], v141 offset:35840
	ds_read_b128 v[178:181], v141 offset:36864
	ds_read_b128 v[182:185], v141 offset:37888
	ds_read_b128 v[186:189], v141 offset:38912
	ds_read_b128 v[190:193], v141 offset:39936
	global_load_lds_dwordx4 v[194:195], off
	v_lshl_add_u64 v[194:195], s[16:17], 0, v[130:131]
	s_mov_b32 m0, s26
	s_nop 0
	global_load_lds_dwordx4 v[194:195], off
	s_waitcnt lgkmcnt(8)
	s_barrier
	s_waitcnt lgkmcnt(0)
	s_setprio 1
	v_mfma_f32_16x16x32_bf16 v[124:127], v[142:145], v[158:161], v[124:127]
	v_mfma_f32_16x16x32_bf16 v[120:123], v[150:153], v[158:161], v[120:123]
	v_mfma_f32_16x16x32_bf16 v[116:119], v[142:145], v[166:169], v[116:119]
	v_mfma_f32_16x16x32_bf16 v[112:115], v[150:153], v[166:169], v[112:115]
	v_mfma_f32_16x16x32_bf16 v[100:103], v[142:145], v[178:181], v[100:103]
	v_mfma_f32_16x16x32_bf16 v[96:99], v[150:153], v[178:181], v[96:99]
	v_mfma_f32_16x16x32_bf16 v[84:87], v[142:145], v[186:189], v[84:87]
	v_mfma_f32_16x16x32_bf16 v[80:83], v[150:153], v[186:189], v[80:83]
	v_mfma_f32_16x16x32_bf16 v[124:127], v[146:149], v[162:165], v[124:127]
	v_mfma_f32_16x16x32_bf16 v[120:123], v[154:157], v[162:165], v[120:123]
	v_mfma_f32_16x16x32_bf16 v[116:119], v[146:149], v[170:173], v[116:119]
	v_mfma_f32_16x16x32_bf16 v[112:115], v[154:157], v[170:173], v[112:115]
	v_mfma_f32_16x16x32_bf16 v[100:103], v[146:149], v[182:185], v[100:103]
	v_mfma_f32_16x16x32_bf16 v[96:99], v[154:157], v[182:185], v[96:99]
	v_mfma_f32_16x16x32_bf16 v[84:87], v[146:149], v[190:193], v[84:87]
	v_mfma_f32_16x16x32_bf16 v[80:83], v[154:157], v[190:193], v[80:83]
	s_setprio 0
	s_barrier
	s_add_i32 s16, 0, 0x1c000
	s_add_i32 s17, s46, s20
	v_add_u32_e32 v206, s16, v139
	v_lshl_add_u64 v[174:175], v[174:175], 0, s[86:87]
	s_mov_b32 m0, s17
	ds_read_b128 v[194:197], v206
	ds_read_b128 v[198:201], v206 offset:1024
	ds_read_b128 v[202:205], v206 offset:2048
	ds_read_b128 v[206:209], v206 offset:3072
	global_load_lds_dwordx4 v[174:175], off
	v_lshl_add_u64 v[174:175], v[210:211], 0, s[86:87]
	s_add_i32 m0, s17, 0x2000
	s_nop 0
	global_load_lds_dwordx4 v[174:175], off
	s_barrier
	s_waitcnt lgkmcnt(0)
	s_setprio 1
	v_mfma_f32_16x16x32_bf16 v[108:111], v[194:197], v[158:161], v[108:111]
	v_mfma_f32_16x16x32_bf16 v[104:107], v[202:205], v[158:161], v[104:107]
	v_mfma_f32_16x16x32_bf16 v[92:95], v[194:197], v[166:169], v[92:95]
	v_mfma_f32_16x16x32_bf16 v[88:91], v[202:205], v[166:169], v[88:91]
	v_mfma_f32_16x16x32_bf16 v[76:79], v[194:197], v[178:181], v[76:79]
	v_mfma_f32_16x16x32_bf16 v[72:75], v[202:205], v[178:181], v[72:75]
	v_mfma_f32_16x16x32_bf16 v[68:71], v[194:197], v[186:189], v[68:71]
	v_mfma_f32_16x16x32_bf16 v[64:67], v[202:205], v[186:189], v[64:67]
	v_mfma_f32_16x16x32_bf16 v[108:111], v[198:201], v[162:165], v[108:111]
	v_mfma_f32_16x16x32_bf16 v[104:107], v[206:209], v[162:165], v[104:107]
	v_mfma_f32_16x16x32_bf16 v[92:95], v[198:201], v[170:173], v[92:95]
	v_mfma_f32_16x16x32_bf16 v[88:91], v[206:209], v[170:173], v[88:91]
	v_mfma_f32_16x16x32_bf16 v[76:79], v[198:201], v[182:185], v[76:79]
	v_mfma_f32_16x16x32_bf16 v[72:75], v[206:209], v[182:185], v[72:75]
	v_mfma_f32_16x16x32_bf16 v[68:71], v[198:201], v[190:193], v[68:71]
	v_mfma_f32_16x16x32_bf16 v[64:67], v[206:209], v[190:193], v[64:67]
	s_setprio 0
	s_mov_b32 m0, s28
	v_lshl_add_u64 v[174:175], v[212:213], 0, s[86:87]
	s_barrier
	ds_read_b128 v[158:161], v141 offset:49152
	ds_read_b128 v[162:165], v141 offset:50176
	ds_read_b128 v[166:169], v141 offset:51200
	ds_read_b128 v[170:173], v141 offset:52224
	ds_read_b128 v[178:181], v141 offset:53248
	ds_read_b128 v[182:185], v141 offset:54272
	ds_read_b128 v[186:189], v141 offset:55296
	ds_read_b128 v[190:193], v141 offset:56320
	global_load_lds_dwordx4 v[174:175], off
	v_lshl_add_u64 v[174:175], v[214:215], 0, s[86:87]
	s_mov_b32 m0, s29
	s_nop 0
	global_load_lds_dwordx4 v[174:175], off
	s_barrier
; #define PG8_STAGE(bufoff, gbase, voff) do { _Pragma("unroll") for (int _i = 0; _i < 2; ++_i) \
;         __builtin_amdgcn_global_load_lds((const unsigned*)((const char*)(gbase) + (voff)[_i]), (PG8_LAS unsigned*)(lds + (bufoff) + ldsw + _i * 8192), 16, 0, 0); } while (0)
; #define PG8_MMA(ai, bj, At, Bt) do { __builtin_amdgcn_s_setprio(1); _Pragma("unroll") for (int m = 0; m < 4; ++m) _Pragma("unroll") for (int n = 0; n < 2; ++n) _Pragma("unroll") for (int k = 0; k < 2; ++k) \
;         acc[ai][bj][m][n] = __builtin_amdgcn_mfma_f32_16x16x32_bf16(Bt[n][k], At[m][k], acc[ai][bj][m][n], 0, 0, 0); __builtin_amdgcn_s_setprio(0); } while (0)
; #define PG8_WAIT_V(n) asm volatile("s_waitcnt vmcnt(" #n ")" ::: "memory")
; #define PG8_WAIT_L(n) asm volatile("s_waitcnt lgkmcnt(" #n ")" ::: "memory")
; #define PG8_BAR __builtin_amdgcn_s_barrier()
; #define PG8_SCHED __builtin_amdgcn_sched_barrier(0)
; template <class Epi, class Sched>
; __device__ __forceinline__ void gemm_phase(PG8_LAS unsigned char* lds, const Gemm g, const Sched& S, const Epi& E) {
;     ...
;             PG8_BAR; PG8_WAIT_L(0); PG8_MMA(1, 0, At, B0); PG8_BAR; PG8_SCHED;
;             PG8_STAGE(PG8_SB(1, 1), b3 + hstep, voffB);
;             PG8_WAIT_V(6); PG8_BAR; PG8_MMA(1, 1, At, B1); PG8_BAR;
;         }
	s_waitcnt lgkmcnt(0)
	s_setprio 1
	v_mfma_f32_16x16x32_bf16 v[60:63], v[142:145], v[158:161], v[60:63]
	v_mfma_f32_16x16x32_bf16 v[56:59], v[150:153], v[158:161], v[56:59]
	v_mfma_f32_16x16x32_bf16 v[52:55], v[142:145], v[166:169], v[52:55]
	v_mfma_f32_16x16x32_bf16 v[48:51], v[150:153], v[166:169], v[48:51]
	v_mfma_f32_16x16x32_bf16 v[36:39], v[142:145], v[178:181], v[36:39]
	v_mfma_f32_16x16x32_bf16 v[32:35], v[150:153], v[178:181], v[32:35]
	v_mfma_f32_16x16x32_bf16 v[20:23], v[142:145], v[186:189], v[20:23]
	v_mfma_f32_16x16x32_bf16 v[16:19], v[150:153], v[186:189], v[16:19]
	v_mfma_f32_16x16x32_bf16 v[60:63], v[146:149], v[162:165], v[60:63]
	v_mfma_f32_16x16x32_bf16 v[56:59], v[154:157], v[162:165], v[56:59]
	v_mfma_f32_16x16x32_bf16 v[52:55], v[146:149], v[170:173], v[52:55]
	v_mfma_f32_16x16x32_bf16 v[48:51], v[154:157], v[170:173], v[48:51]
	v_mfma_f32_16x16x32_bf16 v[36:39], v[146:149], v[182:185], v[36:39]
	v_mfma_f32_16x16x32_bf16 v[32:35], v[154:157], v[182:185], v[32:35]
	v_mfma_f32_16x16x32_bf16 v[20:23], v[146:149], v[190:193], v[20:23]
	v_mfma_f32_16x16x32_bf16 v[16:19], v[154:157], v[190:193], v[16:19]
	s_setprio 0
	s_barrier
	s_add_u32 s14, s14, 0x40080
	s_addc_u32 s15, s15, 0
	s_add_i32 s16, s16, s20
	v_lshl_add_u64 v[142:143], s[14:15], 0, v[176:177]
	s_mov_b32 m0, s16
	s_nop 0
	global_load_lds_dwordx4 v[142:143], off
	v_lshl_add_u64 v[142:143], s[14:15], 0, v[128:129]
	s_add_i32 m0, s16, 0x2000
	s_nop 0
	global_load_lds_dwordx4 v[142:143], off
	s_waitcnt vmcnt(6)
	s_barrier
	s_setprio 1
	v_mfma_f32_16x16x32_bf16 v[44:47], v[194:197], v[158:161], v[44:47]
	v_mfma_f32_16x16x32_bf16 v[40:43], v[202:205], v[158:161], v[40:43]
	v_mfma_f32_16x16x32_bf16 v[28:31], v[194:197], v[166:169], v[28:31]
	v_mfma_f32_16x16x32_bf16 v[24:27], v[202:205], v[166:169], v[24:27]
	v_mfma_f32_16x16x32_bf16 v[12:15], v[194:197], v[178:181], v[12:15]
	v_mfma_f32_16x16x32_bf16 v[8:11], v[202:205], v[178:181], v[8:11]
	v_mfma_f32_16x16x32_bf16 v[4:7], v[194:197], v[186:189], v[4:7]
	v_mfma_f32_16x16x32_bf16 v[0:3], v[202:205], v[186:189], v[0:3]
	v_mfma_f32_16x16x32_bf16 v[44:47], v[198:201], v[162:165], v[44:47]
	v_mfma_f32_16x16x32_bf16 v[40:43], v[206:209], v[162:165], v[40:43]
	v_mfma_f32_16x16x32_bf16 v[28:31], v[198:201], v[170:173], v[28:31]
	v_mfma_f32_16x16x32_bf16 v[24:27], v[206:209], v[170:173], v[24:27]
	v_mfma_f32_16x16x32_bf16 v[12:15], v[198:201], v[182:185], v[12:15]
	v_mfma_f32_16x16x32_bf16 v[8:11], v[206:209], v[182:185], v[8:11]
	v_mfma_f32_16x16x32_bf16 v[4:7], v[198:201], v[190:193], v[4:7]
	v_mfma_f32_16x16x32_bf16 v[0:3], v[206:209], v[190:193], v[0:3]
	s_setprio 0
	s_add_i32 s45, s45, 2
	s_add_u32 s12, s12, 0x100
	s_addc_u32 s13, s13, 0
	s_add_u32 s43, s43, 0x100
	s_addc_u32 s44, s44, 0
	s_cmp_gt_u32 s45, 13
	s_barrier
	s_cbranch_scc0 .LBB0_137
; __device__ __forceinline__ unsigned cvtpk(float lo, float hi) { const f32x2 v = (f32x2){lo, hi}; const bf16v2 b = __builtin_convertvector(v, bf16v2); return __builtin_bit_cast(unsigned, b); }
; #define PG8_WAIT_V(n) asm volatile("s_waitcnt vmcnt(" #n ")" ::: "memory")
; #define PG8_BAR __builtin_amdgcn_s_barrier()
; template <class Epi, class Sched>
; __device__ __forceinline__ void gemm_phase(PG8_LAS unsigned char* lds, const Gemm g, const Sched& S, const Epi& E) {
;     ...
;         if constexpr (!Epi::AFTER_DRAIN) { E(acc, cur, wr, wc, fr, fq); S.done(cur); }
;         if (!has_next) break;
; #pragma unroll
;         for (int a = 0; a < 2; ++a)
; #pragma unroll
;             for (int b = 0; b < 2; ++b)
; #pragma unroll
;                 for (int m = 0; m < 4; ++m)
; #pragma unroll
;                     for (int n = 0; n < 2; ++n) acc[a][b][m][n] = (f32x4){0.f, 0.f, 0.f, 0.f};
;         cur = nxt; cA = nA; cB = nB; ++ui;
;     }
;     PG8_WAIT_V(0);
;     if (wr == 0) PG8_BAR;
;     __device__ __forceinline__ void operator()(const f32x4 (&acc)[2][2][4][2], const pg8::Unit& u, int wr, int wc, int fr, int fq) const {
;         const int row0 = u.pm * 256 + wr * 64 + fr, col0 = u.pn * 256 + wc * 32 + 8 * fq;
; #pragma unroll
;         for (int ai = 0; ai < 2; ++ai)
; #pragma unroll
;             for (int m = 0; m < 4; ++m) { bf16_t* rowp = O + (size_t)(row0 + ai * 128 + m * 16) * ldc + col0;
; #pragma unroll
;                 for (int bj = 0; bj < 2; ++bj) { const f32x4 v0 = acc[ai][bj][m][0], v1 = acc[ai][bj][m][1];
;                     u32x4 w; w.x = cvtpk(v0[0], v0[1]); w.y = cvtpk(v0[2], v0[3]); w.z = cvtpk(v1[0], v1[1]); w.w = cvtpk(v1[2], v1[3]);
;                     *(u32x4*)(rowp + bj * 128) = w; } }
;     }
	v_lshl_add_u32 v142, s0, 8, v138
	v_lshl_or_b32 v144, s34, 8, v140
	v_ashrrev_i32_e32 v143, 31, v142
	v_readlane_b32 s12, v253, 18
	v_ashrrev_i32_e32 v145, 31, v144
	v_lshlrev_b64 v[146:147], 11, v[142:143]
	v_readlane_b32 s13, v253, 19
	v_cvt_pk_bf16_f32 v108, v108, v109
	v_cvt_pk_bf16_f32 v109, v110, v111
	v_cvt_pk_bf16_f32 v110, v104, v105
	v_or_b32_e32 v104, 16, v142
	v_cvt_pk_bf16_f32 v92, v92, v93
	v_cvt_pk_bf16_f32 v93, v94, v95
	v_cvt_pk_bf16_f32 v94, v88, v89
	v_or_b32_e32 v88, 32, v142
	v_cvt_pk_bf16_f32 v76, v76, v77
	v_cvt_pk_bf16_f32 v77, v78, v79
	v_cvt_pk_bf16_f32 v78, v72, v73
	v_or_b32_e32 v72, 48, v142
	v_lshl_add_u64 v[146:147], s[12:13], 0, v[146:147]
	v_lshlrev_b64 v[144:145], 1, v[144:145]
	v_ashrrev_i32_e32 v105, 31, v104
	v_ashrrev_i32_e32 v89, 31, v88
	v_ashrrev_i32_e32 v73, 31, v72
	v_lshl_add_u64 v[146:147], v[146:147], 0, v[144:145]
	v_lshlrev_b64 v[104:105], 11, v[104:105]
	v_lshlrev_b64 v[88:89], 11, v[88:89]
	v_lshlrev_b64 v[72:73], 11, v[72:73]
	v_lshl_add_u64 v[104:105], s[12:13], 0, v[104:105]
	v_lshl_add_u64 v[88:89], s[12:13], 0, v[88:89]
	v_lshl_add_u64 v[72:73], s[12:13], 0, v[72:73]
	s_mov_b64 s[12:13], 0x40000
	v_cvt_pk_bf16_f32 v60, v60, v61
	v_cvt_pk_bf16_f32 v61, v62, v63
	v_cvt_pk_bf16_f32 v62, v56, v57
	v_add_co_u32_e32 v56, vcc, s2, v146
	v_cvt_pk_bf16_f32 v68, v68, v69
	v_cvt_pk_bf16_f32 v69, v70, v71
	v_cvt_pk_bf16_f32 v70, v64, v65
	v_lshl_add_u64 v[64:65], v[146:147], 0, s[12:13]
	v_addc_co_u32_e32 v57, vcc, 0, v147, vcc
	v_cvt_pk_bf16_f32 v44, v44, v45
	v_cvt_pk_bf16_f32 v45, v46, v47
	v_cvt_pk_bf16_f32 v46, v40, v41
	v_cvt_pk_bf16_f32 v47, v42, v43
	s_mov_b32 s0, 0x48000
	global_store_dwordx4 v[64:65], v[44:47], off offset:256
	s_mov_b64 s[12:13], 0x48000
	v_cvt_pk_bf16_f32 v28, v28, v29
	v_add_co_u32_e32 v46, vcc, s0, v146
	v_lshl_add_u64 v[44:45], v[146:147], 0, s[12:13]
	s_nop 0
	v_addc_co_u32_e32 v47, vcc, 0, v147, vcc
	v_cvt_pk_bf16_f32 v29, v30, v31
	v_cvt_pk_bf16_f32 v30, v24, v25
	v_cvt_pk_bf16_f32 v31, v26, v27
	s_mov_b32 s0, 0x50000
	global_store_dwordx4 v[44:45], v[28:31], off offset:256
	s_mov_b64 s[12:13], 0x50000
	v_cvt_pk_bf16_f32 v111, v106, v107
	v_add_co_u32_e32 v30, vcc, s0, v146
	v_lshl_add_u64 v[28:29], v[146:147], 0, s[12:13]
	s_nop 0
	v_addc_co_u32_e32 v31, vcc, 0, v147, vcc
	v_cvt_pk_bf16_f32 v12, v12, v13
	v_cvt_pk_bf16_f32 v13, v14, v15
	v_cvt_pk_bf16_f32 v14, v8, v9
	v_cvt_pk_bf16_f32 v15, v10, v11
	s_mov_b32 s0, 0x58000
	global_store_dwordx4 v[146:147], v[108:111], off offset:256
	v_cvt_pk_bf16_f32 v95, v90, v91
	global_store_dwordx4 v[28:29], v[12:15], off offset:256
	v_lshl_add_u64 v[108:109], v[104:105], 0, v[144:145]
	global_store_dwordx4 v[108:109], v[92:95], off offset:256
	v_add_co_u32_e32 v14, vcc, s0, v146
	s_nop 0
	v_lshl_add_u64 v[92:93], v[88:89], 0, v[144:145]
	v_cvt_pk_bf16_f32 v79, v74, v75
	s_mov_b64 s[12:13], 0x58000
	v_addc_co_u32_e32 v15, vcc, 0, v147, vcc
	v_cvt_pk_bf16_f32 v124, v124, v125
	v_cvt_pk_bf16_f32 v125, v126, v127
	v_cvt_pk_bf16_f32 v126, v120, v121
	v_cvt_pk_bf16_f32 v127, v122, v123
	v_cvt_pk_bf16_f32 v104, v116, v117
	v_cvt_pk_bf16_f32 v105, v118, v119
	v_cvt_pk_bf16_f32 v106, v112, v113
	v_cvt_pk_bf16_f32 v107, v114, v115
	v_cvt_pk_bf16_f32 v88, v100, v101
	v_cvt_pk_bf16_f32 v89, v102, v103
	v_cvt_pk_bf16_f32 v90, v96, v97
	v_cvt_pk_bf16_f32 v91, v98, v99
	global_store_dwordx4 v[92:93], v[76:79], off offset:256
	v_cvt_pk_bf16_f32 v74, v80, v81
	v_cvt_pk_bf16_f32 v75, v82, v83
	v_lshl_add_u64 v[76:77], v[72:73], 0, v[144:145]
	v_cvt_pk_bf16_f32 v72, v84, v85
	v_cvt_pk_bf16_f32 v73, v86, v87
	v_cvt_pk_bf16_f32 v71, v66, v67
	v_cvt_pk_bf16_f32 v63, v58, v59
	v_cvt_pk_bf16_f32 v40, v52, v53
	v_cvt_pk_bf16_f32 v41, v54, v55
	v_cvt_pk_bf16_f32 v42, v48, v49
	v_cvt_pk_bf16_f32 v43, v50, v51
	v_cvt_pk_bf16_f32 v24, v36, v37
	v_cvt_pk_bf16_f32 v25, v38, v39
	v_cvt_pk_bf16_f32 v26, v32, v33
	v_cvt_pk_bf16_f32 v27, v34, v35
	v_lshl_add_u64 v[12:13], v[146:147], 0, s[12:13]
	v_cvt_pk_bf16_f32 v8, v20, v21
	v_cvt_pk_bf16_f32 v9, v22, v23
	v_cvt_pk_bf16_f32 v10, v16, v17
	v_cvt_pk_bf16_f32 v11, v18, v19
	v_cvt_pk_bf16_f32 v4, v4, v5
	v_cvt_pk_bf16_f32 v5, v6, v7
	v_cvt_pk_bf16_f32 v6, v0, v1
	v_cvt_pk_bf16_f32 v7, v2, v3
	s_and_b64 vcc, exec, s[38:39]
	s_mov_b32 s34, s4
	s_mov_b32 s0, s6
	s_mov_b64 s[14:15], s[10:11]
	s_mov_b64 s[12:13], s[8:9]
	global_store_dwordx4 v[146:147], v[124:127], off
	global_store_dwordx4 v[108:109], v[104:107], off
	global_store_dwordx4 v[92:93], v[88:91], off
	global_store_dwordx4 v[76:77], v[72:75], off
	global_store_dwordx4 v[76:77], v[68:71], off offset:256
	global_store_dwordx4 v[56:57], v[60:63], off
	global_store_dwordx4 v[46:47], v[40:43], off
	global_store_dwordx4 v[30:31], v[24:27], off
	global_store_dwordx4 v[14:15], v[8:11], off
	global_store_dwordx4 v[12:13], v[4:7], off offset:256
	s_cbranch_vccz .LBB0_134
	s_waitcnt vmcnt(0)
	v_readlane_b32 s22, v255, 14
	s_cmpk_gt_u32 s19, 0xff
	v_readlane_b32 s23, v255, 15
	s_mov_b64 s[28:29], s[54:55]
	s_cbranch_scc1 .LBB0_141
	s_barrier

; #define PG8_STAGE(bufoff, gbase, voff) do { _Pragma("unroll") for (int _i = 0; _i < 2; ++_i) \
;         __builtin_amdgcn_global_load_lds((const unsigned*)((const char*)(gbase) + (voff)[_i]), (PG8_LAS unsigned*)(lds + (bufoff) + ldsw + _i * 8192), 16, 0, 0); } while (0)
; #define PG8_LDA(dst, b, h) do { _Pragma("unroll") for (int m = 0; m < 4; ++m) _Pragma("unroll") for (int k = 0; k < 2; ++k) dst[m][k] = *(const PG8_LAS bf16x8*)(lds + PG8_SA(b, h) + aoff + m * 2048 + k * 1024); } while (0)
; #define PG8_LDB(dst, b, h) do { _Pragma("unroll") for (int n = 0; n < 2; ++n) _Pragma("unroll") for (int k = 0; k < 2; ++k) dst[n][k] = *(const PG8_LAS bf16x8*)(lds + PG8_SB(b, h) + boff + n * 2048 + k * 1024); } while (0)
; #define PG8_MMA(ai, bj, At, Bt) do { __builtin_amdgcn_s_setprio(1); _Pragma("unroll") for (int m = 0; m < 4; ++m) _Pragma("unroll") for (int n = 0; n < 2; ++n) _Pragma("unroll") for (int k = 0; k < 2; ++k) \
;         acc[ai][bj][m][n] = __builtin_amdgcn_mfma_f32_16x16x32_bf16(Bt[n][k], At[m][k], acc[ai][bj][m][n], 0, 0, 0); __builtin_amdgcn_s_setprio(0); } while (0)
; #define PG8_WAIT_L(n) asm volatile("s_waitcnt lgkmcnt(" #n ")" ::: "memory")
; #define PG8_BAR __builtin_amdgcn_s_barrier()
; #define PG8_SCHED __builtin_amdgcn_sched_barrier(0)
; template <class Epi, class Sched>
; __device__ __forceinline__ void gemm_phase(PG8_LAS unsigned char* lds, const Gemm g, const Sched& S, const Epi& E) {
;     ...
;         for (int t = 0; t < nt; t += 2) {
;             const bool last = (t == nt - 2);
;             const char* a1 = cA + (size_t)(t + 1) * kstep;
;             const char* a2 = last ? nA : cA + (size_t)(t + 2) * kstep; const char* b2 = last ? nB : cB + (size_t)(t + 2) * kstep;
;             const char* a3 = a2 + kstep; const char* b3 = b2 + kstep;
;             if (last && has_next) S.a_ready(nxt);
;             PG8_LDB(B0, 0, 0); PG8_SCHED; PG8_LDA(At, 0, 0); PG8_STAGE(PG8_SA(1, 1), a1 + hstep, voffA);
;             PG8_WAIT_L(8); PG8_BAR; PG8_WAIT_L(0); PG8_MMA(0, 0, At, B0); PG8_BAR; PG8_SCHED;
;             PG8_LDB(B1, 0, 1); PG8_STAGE(PG8_SB(0, 0), b2, voffB);
;             PG8_BAR; PG8_WAIT_L(0); PG8_MMA(0, 1, At, B1); PG8_BAR;
;             PG8_LDA(At, 0, 1); PG8_STAGE(PG8_SA(0, 0), a2, voffA);
;             PG8_BAR; PG8_WAIT_L(0); PG8_MMA(1, 0, At, B0); PG8_BAR; PG8_SCHED;
.LBB0_358:
	s_add_u32 s14, s12, 0xfffc0080
	s_addc_u32 s15, s13, -1
	s_add_i32 s46, 0, 0x10000
	v_add_u32_e32 v154, s46, v139
	ds_read_b128 v[142:145], v154
	ds_read_b128 v[146:149], v154 offset:1024
	ds_read_b128 v[150:153], v154 offset:2048
	ds_read_b128 v[154:157], v154 offset:3072
	s_cmp_eq_u32 s45, 12
	s_cselect_b32 s17, s7, s15
	s_cselect_b32 s16, s40, s14
	s_cselect_b32 s15, s5, s44
	s_cselect_b32 s14, s41, s43
	v_lshl_add_u64 v[174:175], s[12:13], 0, v[134:135]
	s_add_i32 m0, s1, 0xc000
	ds_read_b128 v[158:161], v141
	ds_read_b128 v[162:165], v141 offset:1024
	ds_read_b128 v[166:169], v141 offset:2048
	ds_read_b128 v[170:173], v141 offset:3072
	ds_read_b128 v[182:185], v141 offset:4096
	ds_read_b128 v[190:193], v141 offset:5120
	ds_read_b128 v[194:197], v141 offset:6144
	ds_read_b128 v[198:201], v141 offset:7168
	global_load_lds_dwordx4 v[174:175], off
	v_lshl_add_u64 v[174:175], s[12:13], 0, v[136:137]
	s_add_i32 m0, s1, 0xe000
	s_nop 0
	global_load_lds_dwordx4 v[174:175], off
	s_waitcnt lgkmcnt(8)
	s_barrier
	s_waitcnt lgkmcnt(0)
	s_setprio 1
	v_mfma_f32_16x16x32_bf16 v[124:127], v[142:145], v[158:161], v[124:127]
	v_mfma_f32_16x16x32_bf16 v[120:123], v[150:153], v[158:161], v[120:123]
	v_mfma_f32_16x16x32_bf16 v[116:119], v[142:145], v[166:169], v[116:119]
	v_mfma_f32_16x16x32_bf16 v[112:115], v[150:153], v[166:169], v[112:115]
	v_mfma_f32_16x16x32_bf16 v[100:103], v[142:145], v[182:185], v[100:103]
	v_mfma_f32_16x16x32_bf16 v[96:99], v[150:153], v[182:185], v[96:99]
	v_mfma_f32_16x16x32_bf16 v[84:87], v[142:145], v[194:197], v[84:87]
	v_mfma_f32_16x16x32_bf16 v[80:83], v[150:153], v[194:197], v[80:83]
	v_mfma_f32_16x16x32_bf16 v[124:127], v[146:149], v[162:165], v[124:127]
	v_mfma_f32_16x16x32_bf16 v[120:123], v[154:157], v[162:165], v[120:123]
	v_mfma_f32_16x16x32_bf16 v[116:119], v[146:149], v[170:173], v[116:119]
	v_mfma_f32_16x16x32_bf16 v[112:115], v[154:157], v[170:173], v[112:115]
	v_mfma_f32_16x16x32_bf16 v[100:103], v[146:149], v[190:193], v[100:103]
	v_mfma_f32_16x16x32_bf16 v[96:99], v[154:157], v[190:193], v[96:99]
	v_mfma_f32_16x16x32_bf16 v[84:87], v[146:149], v[198:201], v[84:87]
	v_mfma_f32_16x16x32_bf16 v[80:83], v[154:157], v[198:201], v[80:83]
	s_setprio 0
	s_barrier
	s_add_i32 s48, 0, 0x14000
	v_add_u32_e32 v174, s48, v139
	s_add_i32 s46, s46, s20
	ds_read_b128 v[202:205], v174
	ds_read_b128 v[206:209], v174 offset:1024
	ds_read_b128 v[210:213], v174 offset:2048
	ds_read_b128 v[214:217], v174 offset:3072
	v_lshl_add_u64 v[174:175], s[14:15], 0, v[176:177]
	s_mov_b32 m0, s46
	v_lshl_add_u64 v[178:179], s[14:15], 0, v[128:129]
	global_load_lds_dwordx4 v[174:175], off
	s_add_i32 m0, s46, 0x2000
	s_nop 0
	global_load_lds_dwordx4 v[178:179], off
	s_barrier
	s_waitcnt lgkmcnt(0)
	s_setprio 1
	v_mfma_f32_16x16x32_bf16 v[108:111], v[202:205], v[158:161], v[108:111]
	v_mfma_f32_16x16x32_bf16 v[104:107], v[210:213], v[158:161], v[104:107]
	v_mfma_f32_16x16x32_bf16 v[92:95], v[202:205], v[166:169], v[92:95]
	v_mfma_f32_16x16x32_bf16 v[88:91], v[210:213], v[166:169], v[88:91]
	v_mfma_f32_16x16x32_bf16 v[76:79], v[202:205], v[182:185], v[76:79]
	v_mfma_f32_16x16x32_bf16 v[72:75], v[210:213], v[182:185], v[72:75]
	v_mfma_f32_16x16x32_bf16 v[68:71], v[202:205], v[194:197], v[68:71]
	v_mfma_f32_16x16x32_bf16 v[64:67], v[210:213], v[194:197], v[64:67]
	v_mfma_f32_16x16x32_bf16 v[108:111], v[206:209], v[162:165], v[108:111]
	v_mfma_f32_16x16x32_bf16 v[104:107], v[214:217], v[162:165], v[104:107]
	v_mfma_f32_16x16x32_bf16 v[92:95], v[206:209], v[170:173], v[92:95]
	v_mfma_f32_16x16x32_bf16 v[88:91], v[214:217], v[170:173], v[88:91]
	v_mfma_f32_16x16x32_bf16 v[76:79], v[206:209], v[190:193], v[76:79]
	v_mfma_f32_16x16x32_bf16 v[72:75], v[214:217], v[190:193], v[72:75]
	v_mfma_f32_16x16x32_bf16 v[68:71], v[206:209], v[198:201], v[68:71]
	v_mfma_f32_16x16x32_bf16 v[64:67], v[214:217], v[198:201], v[64:67]
	s_setprio 0
	s_mov_b32 m0, s1
	v_lshl_add_u64 v[180:181], s[16:17], 0, v[132:133]
	s_barrier
	ds_read_b128 v[158:161], v141 offset:16384
	ds_read_b128 v[162:165], v141 offset:17408
	ds_read_b128 v[166:169], v141 offset:18432
	ds_read_b128 v[170:173], v141 offset:19456
	ds_read_b128 v[182:185], v141 offset:20480
	ds_read_b128 v[190:193], v141 offset:21504
	ds_read_b128 v[194:197], v141 offset:22528
	ds_read_b128 v[198:201], v141 offset:23552
	global_load_lds_dwordx4 v[180:181], off
	v_lshl_add_u64 v[186:187], s[16:17], 0, v[130:131]
	s_mov_b32 m0, s22
	s_nop 0
	global_load_lds_dwordx4 v[186:187], off
	s_barrier
	s_waitcnt lgkmcnt(0)
	s_setprio 1
	v_mfma_f32_16x16x32_bf16 v[60:63], v[142:145], v[158:161], v[60:63]
	v_mfma_f32_16x16x32_bf16 v[56:59], v[150:153], v[158:161], v[56:59]
	v_mfma_f32_16x16x32_bf16 v[52:55], v[142:145], v[166:169], v[52:55]
	v_mfma_f32_16x16x32_bf16 v[48:51], v[150:153], v[166:169], v[48:51]
	v_mfma_f32_16x16x32_bf16 v[36:39], v[142:145], v[182:185], v[36:39]
	v_mfma_f32_16x16x32_bf16 v[32:35], v[150:153], v[182:185], v[32:35]
	v_mfma_f32_16x16x32_bf16 v[20:23], v[142:145], v[194:197], v[20:23]
	v_mfma_f32_16x16x32_bf16 v[16:19], v[150:153], v[194:197], v[16:19]
	v_mfma_f32_16x16x32_bf16 v[60:63], v[146:149], v[162:165], v[60:63]
	v_mfma_f32_16x16x32_bf16 v[56:59], v[154:157], v[162:165], v[56:59]
	v_mfma_f32_16x16x32_bf16 v[52:55], v[146:149], v[170:173], v[52:55]
	v_mfma_f32_16x16x32_bf16 v[48:51], v[154:157], v[170:173], v[48:51]
	v_mfma_f32_16x16x32_bf16 v[36:39], v[146:149], v[190:193], v[36:39]
	v_mfma_f32_16x16x32_bf16 v[32:35], v[154:157], v[190:193], v[32:35]
	v_mfma_f32_16x16x32_bf16 v[20:23], v[146:149], v[198:201], v[20:23]
	v_mfma_f32_16x16x32_bf16 v[16:19], v[154:157], v[198:201], v[16:19]
	s_setprio 0
	s_barrier
; #define PG8_STAGE(bufoff, gbase, voff) do { _Pragma("unroll") for (int _i = 0; _i < 2; ++_i) \
;         __builtin_amdgcn_global_load_lds((const unsigned*)((const char*)(gbase) + (voff)[_i]), (PG8_LAS unsigned*)(lds + (bufoff) + ldsw + _i * 8192), 16, 0, 0); } while (0)
; #define PG8_LDA(dst, b, h) do { _Pragma("unroll") for (int m = 0; m < 4; ++m) _Pragma("unroll") for (int k = 0; k < 2; ++k) dst[m][k] = *(const PG8_LAS bf16x8*)(lds + PG8_SA(b, h) + aoff + m * 2048 + k * 1024); } while (0)
; #define PG8_LDB(dst, b, h) do { _Pragma("unroll") for (int n = 0; n < 2; ++n) _Pragma("unroll") for (int k = 0; k < 2; ++k) dst[n][k] = *(const PG8_LAS bf16x8*)(lds + PG8_SB(b, h) + boff + n * 2048 + k * 1024); } while (0)
; #define PG8_MMA(ai, bj, At, Bt) do { __builtin_amdgcn_s_setprio(1); _Pragma("unroll") for (int m = 0; m < 4; ++m) _Pragma("unroll") for (int n = 0; n < 2; ++n) _Pragma("unroll") for (int k = 0; k < 2; ++k) \
;         acc[ai][bj][m][n] = __builtin_amdgcn_mfma_f32_16x16x32_bf16(Bt[n][k], At[m][k], acc[ai][bj][m][n], 0, 0, 0); __builtin_amdgcn_s_setprio(0); } while (0)
; #define PG8_WAIT_V(n) asm volatile("s_waitcnt vmcnt(" #n ")" ::: "memory")
; #define PG8_WAIT_L(n) asm volatile("s_waitcnt lgkmcnt(" #n ")" ::: "memory")
; #define PG8_BAR __builtin_amdgcn_s_barrier()
; #define PG8_SCHED __builtin_amdgcn_sched_barrier(0)
; template <class Epi, class Sched>
; __device__ __forceinline__ void gemm_phase(PG8_LAS unsigned char* lds, const Gemm g, const Sched& S, const Epi& E) {
;     ...
;             PG8_STAGE(PG8_SB(0, 1), b2 + hstep, voffB);
;             PG8_WAIT_V(6); PG8_BAR; PG8_MMA(1, 1, At, B1); PG8_BAR;
;             PG8_LDB(B0, 1, 0); PG8_SCHED; PG8_LDA(At, 1, 0); PG8_STAGE(PG8_SA(0, 1), a2 + hstep, voffA);
;             PG8_WAIT_L(8); PG8_BAR; PG8_WAIT_L(0); PG8_MMA(0, 0, At, B0); PG8_BAR; PG8_SCHED;
;             PG8_LDB(B1, 1, 1); PG8_STAGE(PG8_SB(1, 0), b3, voffB);
;             PG8_BAR; PG8_WAIT_L(0); PG8_MMA(0, 1, At, B1); PG8_BAR;
;             PG8_LDA(At, 1, 1); PG8_STAGE(PG8_SA(1, 0), a3, voffA);
	s_add_u32 s46, s14, 0x40000
	s_addc_u32 s47, s15, 0
	s_add_i32 s48, s48, s20
	v_lshl_add_u64 v[142:143], s[46:47], 0, v[176:177]
	s_mov_b32 m0, s48
	s_nop 0
	global_load_lds_dwordx4 v[142:143], off
	v_lshl_add_u64 v[142:143], s[46:47], 0, v[128:129]
	s_add_i32 m0, s48, 0x2000
	s_nop 0
	global_load_lds_dwordx4 v[142:143], off
	s_waitcnt vmcnt(6)
	s_barrier
	s_setprio 1
	v_mfma_f32_16x16x32_bf16 v[44:47], v[202:205], v[158:161], v[44:47]
	v_mfma_f32_16x16x32_bf16 v[40:43], v[210:213], v[158:161], v[40:43]
	v_mfma_f32_16x16x32_bf16 v[28:31], v[202:205], v[166:169], v[28:31]
	v_mfma_f32_16x16x32_bf16 v[24:27], v[210:213], v[166:169], v[24:27]
	v_mfma_f32_16x16x32_bf16 v[12:15], v[202:205], v[182:185], v[12:15]
	v_mfma_f32_16x16x32_bf16 v[8:11], v[210:213], v[182:185], v[8:11]
	v_mfma_f32_16x16x32_bf16 v[4:7], v[202:205], v[194:197], v[4:7]
	v_mfma_f32_16x16x32_bf16 v[0:3], v[210:213], v[194:197], v[0:3]
	v_mfma_f32_16x16x32_bf16 v[44:47], v[206:209], v[162:165], v[44:47]
	v_mfma_f32_16x16x32_bf16 v[40:43], v[214:217], v[162:165], v[40:43]
	v_mfma_f32_16x16x32_bf16 v[28:31], v[206:209], v[170:173], v[28:31]
	v_mfma_f32_16x16x32_bf16 v[24:27], v[214:217], v[170:173], v[24:27]
	v_mfma_f32_16x16x32_bf16 v[12:15], v[206:209], v[190:193], v[12:15]
	v_mfma_f32_16x16x32_bf16 v[8:11], v[214:217], v[190:193], v[8:11]
	v_mfma_f32_16x16x32_bf16 v[4:7], v[206:209], v[198:201], v[4:7]
	v_mfma_f32_16x16x32_bf16 v[0:3], v[214:217], v[198:201], v[0:3]
	s_setprio 0
	s_add_i32 s46, 0, 0x18000
	v_add_u32_e32 v154, s46, v139
	s_barrier
	ds_read_b128 v[142:145], v154
	ds_read_b128 v[146:149], v154 offset:1024
	ds_read_b128 v[150:153], v154 offset:2048
	ds_read_b128 v[154:157], v154 offset:3072
	s_add_u32 s16, s16, 0x40000
	s_addc_u32 s17, s17, 0
	s_mov_b32 m0, s23
	v_lshl_add_u64 v[188:189], s[16:17], 0, v[132:133]
	ds_read_b128 v[158:161], v141 offset:32768
	ds_read_b128 v[162:165], v141 offset:33792
	ds_read_b128 v[166:169], v141 offset:34816
	ds_read_b128 v[170:173], v141 offset:35840
	ds_read_b128 v[182:185], v141 offset:36864
	ds_read_b128 v[190:193], v141 offset:37888
	ds_read_b128 v[194:197], v141 offset:38912
	ds_read_b128 v[198:201], v141 offset:39936
	global_load_lds_dwordx4 v[188:189], off
	v_lshl_add_u64 v[188:189], s[16:17], 0, v[130:131]
	s_mov_b32 m0, s26
	s_nop 0
	global_load_lds_dwordx4 v[188:189], off
	s_waitcnt lgkmcnt(8)
	s_barrier
	s_waitcnt lgkmcnt(0)
	s_setprio 1
	v_mfma_f32_16x16x32_bf16 v[124:127], v[142:145], v[158:161], v[124:127]
	v_mfma_f32_16x16x32_bf16 v[120:123], v[150:153], v[158:161], v[120:123]
	v_mfma_f32_16x16x32_bf16 v[116:119], v[142:145], v[166:169], v[116:119]
	v_mfma_f32_16x16x32_bf16 v[112:115], v[150:153], v[166:169], v[112:115]
	v_mfma_f32_16x16x32_bf16 v[100:103], v[142:145], v[182:185], v[100:103]
	v_mfma_f32_16x16x32_bf16 v[96:99], v[150:153], v[182:185], v[96:99]
	v_mfma_f32_16x16x32_bf16 v[84:87], v[142:145], v[194:197], v[84:87]
	v_mfma_f32_16x16x32_bf16 v[80:83], v[150:153], v[194:197], v[80:83]
	v_mfma_f32_16x16x32_bf16 v[124:127], v[146:149], v[162:165], v[124:127]
	v_mfma_f32_16x16x32_bf16 v[120:123], v[154:157], v[162:165], v[120:123]
	v_mfma_f32_16x16x32_bf16 v[116:119], v[146:149], v[170:173], v[116:119]
	v_mfma_f32_16x16x32_bf16 v[112:115], v[154:157], v[170:173], v[112:115]
	v_mfma_f32_16x16x32_bf16 v[100:103], v[146:149], v[190:193], v[100:103]
	v_mfma_f32_16x16x32_bf16 v[96:99], v[154:157], v[190:193], v[96:99]
	v_mfma_f32_16x16x32_bf16 v[84:87], v[146:149], v[198:201], v[84:87]
	v_mfma_f32_16x16x32_bf16 v[80:83], v[154:157], v[198:201], v[80:83]
	s_setprio 0
	s_barrier
	s_add_i32 s16, 0, 0x1c000
	s_add_i32 s17, s46, s20
	v_add_u32_e32 v188, s16, v139
	v_lshl_add_u64 v[174:175], v[174:175], 0, s[86:87]
	s_mov_b32 m0, s17
	ds_read_b128 v[202:205], v188
	ds_read_b128 v[206:209], v188 offset:1024
	ds_read_b128 v[210:213], v188 offset:2048
	ds_read_b128 v[214:217], v188 offset:3072
	global_load_lds_dwordx4 v[174:175], off
	v_lshl_add_u64 v[174:175], v[178:179], 0, s[86:87]
	s_add_i32 m0, s17, 0x2000
	s_nop 0
	global_load_lds_dwordx4 v[174:175], off
	s_barrier
	s_waitcnt lgkmcnt(0)
	s_setprio 1
	v_mfma_f32_16x16x32_bf16 v[108:111], v[202:205], v[158:161], v[108:111]
	v_mfma_f32_16x16x32_bf16 v[104:107], v[210:213], v[158:161], v[104:107]
	v_mfma_f32_16x16x32_bf16 v[92:95], v[202:205], v[166:169], v[92:95]
	v_mfma_f32_16x16x32_bf16 v[88:91], v[210:213], v[166:169], v[88:91]
	v_mfma_f32_16x16x32_bf16 v[76:79], v[202:205], v[182:185], v[76:79]
	v_mfma_f32_16x16x32_bf16 v[72:75], v[210:213], v[182:185], v[72:75]
	v_mfma_f32_16x16x32_bf16 v[68:71], v[202:205], v[194:197], v[68:71]
	v_mfma_f32_16x16x32_bf16 v[64:67], v[210:213], v[194:197], v[64:67]
	v_mfma_f32_16x16x32_bf16 v[108:111], v[206:209], v[162:165], v[108:111]
	v_mfma_f32_16x16x32_bf16 v[104:107], v[214:217], v[162:165], v[104:107]
	v_mfma_f32_16x16x32_bf16 v[92:95], v[206:209], v[170:173], v[92:95]
	v_mfma_f32_16x16x32_bf16 v[88:91], v[214:217], v[170:173], v[88:91]
	v_mfma_f32_16x16x32_bf16 v[76:79], v[206:209], v[190:193], v[76:79]
	v_mfma_f32_16x16x32_bf16 v[72:75], v[214:217], v[190:193], v[72:75]
	v_mfma_f32_16x16x32_bf16 v[68:71], v[206:209], v[198:201], v[68:71]
	v_mfma_f32_16x16x32_bf16 v[64:67], v[214:217], v[198:201], v[64:67]
	s_setprio 0
	s_mov_b32 m0, s28
	v_lshl_add_u64 v[174:175], v[180:181], 0, s[86:87]
	s_barrier
	ds_read_b128 v[158:161], v141 offset:49152
	ds_read_b128 v[162:165], v141 offset:50176
	ds_read_b128 v[166:169], v141 offset:51200
	ds_read_b128 v[170:173], v141 offset:52224
	ds_read_b128 v[182:185], v141 offset:53248
	ds_read_b128 v[190:193], v141 offset:54272
	ds_read_b128 v[194:197], v141 offset:55296
	ds_read_b128 v[198:201], v141 offset:56320
	global_load_lds_dwordx4 v[174:175], off
	v_lshl_add_u64 v[174:175], v[186:187], 0, s[86:87]
	s_mov_b32 m0, s29
	s_nop 0
	global_load_lds_dwordx4 v[174:175], off
	s_barrier
; #define PG8_STAGE(bufoff, gbase, voff) do { _Pragma("unroll") for (int _i = 0; _i < 2; ++_i) \
;         __builtin_amdgcn_global_load_lds((const unsigned*)((const char*)(gbase) + (voff)[_i]), (PG8_LAS unsigned*)(lds + (bufoff) + ldsw + _i * 8192), 16, 0, 0); } while (0)
; #define PG8_MMA(ai, bj, At, Bt) do { __builtin_amdgcn_s_setprio(1); _Pragma("unroll") for (int m = 0; m < 4; ++m) _Pragma("unroll") for (int n = 0; n < 2; ++n) _Pragma("unroll") for (int k = 0; k < 2; ++k) \
;         acc[ai][bj][m][n] = __builtin_amdgcn_mfma_f32_16x16x32_bf16(Bt[n][k], At[m][k], acc[ai][bj][m][n], 0, 0, 0); __builtin_amdgcn_s_setprio(0); } while (0)
; #define PG8_WAIT_V(n) asm volatile("s_waitcnt vmcnt(" #n ")" ::: "memory")
; #define PG8_WAIT_L(n) asm volatile("s_waitcnt lgkmcnt(" #n ")" ::: "memory")
; #define PG8_BAR __builtin_amdgcn_s_barrier()
; #define PG8_SCHED __builtin_amdgcn_sched_barrier(0)
; template <class Epi, class Sched>
; __device__ __forceinline__ void gemm_phase(PG8_LAS unsigned char* lds, const Gemm g, const Sched& S, const Epi& E) {
;     ...
;             PG8_BAR; PG8_WAIT_L(0); PG8_MMA(1, 0, At, B0); PG8_BAR; PG8_SCHED;
;             PG8_STAGE(PG8_SB(1, 1), b3 + hstep, voffB);
;             PG8_WAIT_V(6); PG8_BAR; PG8_MMA(1, 1, At, B1); PG8_BAR;
;         }
	s_waitcnt lgkmcnt(0)
	s_setprio 1
	v_mfma_f32_16x16x32_bf16 v[60:63], v[142:145], v[158:161], v[60:63]
	v_mfma_f32_16x16x32_bf16 v[56:59], v[150:153], v[158:161], v[56:59]
	v_mfma_f32_16x16x32_bf16 v[52:55], v[142:145], v[166:169], v[52:55]
	v_mfma_f32_16x16x32_bf16 v[48:51], v[150:153], v[166:169], v[48:51]
	v_mfma_f32_16x16x32_bf16 v[36:39], v[142:145], v[182:185], v[36:39]
	v_mfma_f32_16x16x32_bf16 v[32:35], v[150:153], v[182:185], v[32:35]
	v_mfma_f32_16x16x32_bf16 v[20:23], v[142:145], v[194:197], v[20:23]
	v_mfma_f32_16x16x32_bf16 v[16:19], v[150:153], v[194:197], v[16:19]
	v_mfma_f32_16x16x32_bf16 v[60:63], v[146:149], v[162:165], v[60:63]
	v_mfma_f32_16x16x32_bf16 v[56:59], v[154:157], v[162:165], v[56:59]
	v_mfma_f32_16x16x32_bf16 v[52:55], v[146:149], v[170:173], v[52:55]
	v_mfma_f32_16x16x32_bf16 v[48:51], v[154:157], v[170:173], v[48:51]
	v_mfma_f32_16x16x32_bf16 v[36:39], v[146:149], v[190:193], v[36:39]
	v_mfma_f32_16x16x32_bf16 v[32:35], v[154:157], v[190:193], v[32:35]
	v_mfma_f32_16x16x32_bf16 v[20:23], v[146:149], v[198:201], v[20:23]
	v_mfma_f32_16x16x32_bf16 v[16:19], v[154:157], v[198:201], v[16:19]
	s_setprio 0
	s_barrier
	s_add_u32 s14, s14, 0x40080
	s_addc_u32 s15, s15, 0
	s_add_i32 s16, s16, s20
	v_lshl_add_u64 v[142:143], s[14:15], 0, v[176:177]
	s_mov_b32 m0, s16
	s_nop 0
	global_load_lds_dwordx4 v[142:143], off
	v_lshl_add_u64 v[142:143], s[14:15], 0, v[128:129]
	s_add_i32 m0, s16, 0x2000
	s_nop 0
	global_load_lds_dwordx4 v[142:143], off
	s_waitcnt vmcnt(6)
	s_barrier
	s_setprio 1
	v_mfma_f32_16x16x32_bf16 v[44:47], v[202:205], v[158:161], v[44:47]
	v_mfma_f32_16x16x32_bf16 v[40:43], v[210:213], v[158:161], v[40:43]
	v_mfma_f32_16x16x32_bf16 v[28:31], v[202:205], v[166:169], v[28:31]
	v_mfma_f32_16x16x32_bf16 v[24:27], v[210:213], v[166:169], v[24:27]
	v_mfma_f32_16x16x32_bf16 v[12:15], v[202:205], v[182:185], v[12:15]
	v_mfma_f32_16x16x32_bf16 v[8:11], v[210:213], v[182:185], v[8:11]
	v_mfma_f32_16x16x32_bf16 v[4:7], v[202:205], v[194:197], v[4:7]
	v_mfma_f32_16x16x32_bf16 v[0:3], v[210:213], v[194:197], v[0:3]
	v_mfma_f32_16x16x32_bf16 v[44:47], v[206:209], v[162:165], v[44:47]
	v_mfma_f32_16x16x32_bf16 v[40:43], v[214:217], v[162:165], v[40:43]
	v_mfma_f32_16x16x32_bf16 v[28:31], v[206:209], v[170:173], v[28:31]
	v_mfma_f32_16x16x32_bf16 v[24:27], v[214:217], v[170:173], v[24:27]
	v_mfma_f32_16x16x32_bf16 v[12:15], v[206:209], v[190:193], v[12:15]
	v_mfma_f32_16x16x32_bf16 v[8:11], v[214:217], v[190:193], v[8:11]
	v_mfma_f32_16x16x32_bf16 v[4:7], v[206:209], v[198:201], v[4:7]
	v_mfma_f32_16x16x32_bf16 v[0:3], v[214:217], v[198:201], v[0:3]
	s_setprio 0
	s_add_i32 s45, s45, 2
	s_add_u32 s12, s12, 0x100
	s_addc_u32 s13, s13, 0
	s_add_u32 s43, s43, 0x100
	s_addc_u32 s44, s44, 0
	s_cmp_gt_u32 s45, 13
	s_barrier
	s_cbranch_scc0 .LBB0_358
; __device__ __forceinline__ unsigned cvtpk(float lo, float hi) { const f32x2 v = (f32x2){lo, hi}; const bf16v2 b = __builtin_convertvector(v, bf16v2); return __builtin_bit_cast(unsigned, b); }
; #define PG8_WAIT_V(n) asm volatile("s_waitcnt vmcnt(" #n ")" ::: "memory")
; #define PG8_BAR __builtin_amdgcn_s_barrier()
; template <class Epi, class Sched>
; __device__ __forceinline__ void gemm_phase(PG8_LAS unsigned char* lds, const Gemm g, const Sched& S, const Epi& E) {
;     ...
;         if constexpr (!Epi::AFTER_DRAIN) { E(acc, cur, wr, wc, fr, fq); S.done(cur); }
;         if (!has_next) break;
; #pragma unroll
;         for (int a = 0; a < 2; ++a)
; #pragma unroll
;             for (int b = 0; b < 2; ++b)
; #pragma unroll
;                 for (int m = 0; m < 4; ++m)
; #pragma unroll
;                     for (int n = 0; n < 2; ++n) acc[a][b][m][n] = (f32x4){0.f, 0.f, 0.f, 0.f};
;         cur = nxt; cA = nA; cB = nB; ++ui;
;     }
;     PG8_WAIT_V(0);
;     if (wr == 0) PG8_BAR;
;     __device__ __forceinline__ void operator()(const f32x4 (&acc)[2][2][4][2], const pg8::Unit& u, int wr, int wc, int fr, int fq) const {
;         const int row0 = u.pm * 256 + wr * 64 + fr, col0 = u.pn * 256 + wc * 32 + 8 * fq;
; #pragma unroll
;         for (int ai = 0; ai < 2; ++ai)
; #pragma unroll
;             for (int m = 0; m < 4; ++m) { bf16_t* rowp = O + (size_t)(row0 + ai * 128 + m * 16) * ldc + col0;
; #pragma unroll
;                 for (int bj = 0; bj < 2; ++bj) { const f32x4 v0 = acc[ai][bj][m][0], v1 = acc[ai][bj][m][1];
;                     u32x4 w; w.x = cvtpk(v0[0], v0[1]); w.y = cvtpk(v0[2], v0[3]); w.z = cvtpk(v1[0], v1[1]); w.w = cvtpk(v1[2], v1[3]);
;                     *(u32x4*)(rowp + bj * 128) = w; } }
;     }
	v_readlane_b32 s12, v253, 16
	v_lshl_add_u32 v148, s0, 8, v138
	v_lshl_or_b32 v142, s34, 8, v140
	v_readlane_b32 s13, v253, 17
	v_ashrrev_i32_e32 v143, 31, v142
	v_cvt_pk_bf16_f32 v68, v68, v69
	v_mov_b64_e32 v[144:145], s[12:13]
	v_cvt_pk_bf16_f32 v69, v70, v71
	v_cvt_pk_bf16_f32 v70, v64, v65
	v_add_u32_e32 v64, 0x80, v148
	v_mad_i64_i32 v[146:147], s[12:13], v148, s81, v[144:145]
	v_lshlrev_b64 v[142:143], 1, v[142:143]
	v_cvt_pk_bf16_f32 v108, v108, v109
	v_cvt_pk_bf16_f32 v109, v110, v111
	v_cvt_pk_bf16_f32 v110, v104, v105
	v_or_b32_e32 v104, 16, v148
	v_mad_i64_i32 v[64:65], s[12:13], v64, s81, v[144:145]
	v_cvt_pk_bf16_f32 v44, v44, v45
	v_cvt_pk_bf16_f32 v45, v46, v47
	v_cvt_pk_bf16_f32 v46, v40, v41
	v_add_u32_e32 v40, 0x90, v148
	v_lshl_add_u64 v[146:147], v[146:147], 0, v[142:143]
	v_cvt_pk_bf16_f32 v111, v106, v107
	v_mad_i64_i32 v[104:105], s[12:13], v104, s81, v[144:145]
	v_cvt_pk_bf16_f32 v92, v92, v93
	v_cvt_pk_bf16_f32 v93, v94, v95
	v_cvt_pk_bf16_f32 v94, v88, v89
	v_or_b32_e32 v88, 32, v148
	v_lshl_add_u64 v[64:65], v[64:65], 0, v[142:143]
	v_cvt_pk_bf16_f32 v47, v42, v43
	v_mad_i64_i32 v[40:41], s[12:13], v40, s81, v[144:145]
	v_cvt_pk_bf16_f32 v28, v28, v29
	v_cvt_pk_bf16_f32 v29, v30, v31
	v_cvt_pk_bf16_f32 v30, v24, v25
	v_add_u32_e32 v24, 0xa0, v148
	global_store_dwordx4 v[146:147], v[108:111], off offset:256
	v_cvt_pk_bf16_f32 v95, v90, v91
	v_mad_i64_i32 v[88:89], s[12:13], v88, s81, v[144:145]
	v_lshl_add_u64 v[108:109], v[104:105], 0, v[142:143]
	v_cvt_pk_bf16_f32 v76, v76, v77
	v_cvt_pk_bf16_f32 v77, v78, v79
	v_cvt_pk_bf16_f32 v78, v72, v73
	v_or_b32_e32 v72, 48, v148
	global_store_dwordx4 v[64:65], v[44:47], off offset:256
	v_cvt_pk_bf16_f32 v31, v26, v27
	v_mad_i64_i32 v[24:25], s[12:13], v24, s81, v[144:145]
	v_lshl_add_u64 v[44:45], v[40:41], 0, v[142:143]
	v_cvt_pk_bf16_f32 v12, v12, v13
	v_cvt_pk_bf16_f32 v13, v14, v15
	v_cvt_pk_bf16_f32 v14, v8, v9
	v_add_u32_e32 v8, 0xb0, v148
	global_store_dwordx4 v[108:109], v[92:95], off offset:256
	v_cvt_pk_bf16_f32 v79, v74, v75
	v_mad_i64_i32 v[72:73], s[12:13], v72, s81, v[144:145]
	v_lshl_add_u64 v[92:93], v[88:89], 0, v[142:143]
	global_store_dwordx4 v[44:45], v[28:31], off offset:256
	v_cvt_pk_bf16_f32 v15, v10, v11
	v_mad_i64_i32 v[8:9], s[12:13], v8, s81, v[144:145]
	v_lshl_add_u64 v[28:29], v[24:25], 0, v[142:143]
	v_cvt_pk_bf16_f32 v124, v124, v125
	v_cvt_pk_bf16_f32 v125, v126, v127
	v_cvt_pk_bf16_f32 v126, v120, v121
	v_cvt_pk_bf16_f32 v127, v122, v123
	v_cvt_pk_bf16_f32 v104, v116, v117
	v_cvt_pk_bf16_f32 v105, v118, v119
	v_cvt_pk_bf16_f32 v106, v112, v113
	v_cvt_pk_bf16_f32 v107, v114, v115
	v_cvt_pk_bf16_f32 v88, v100, v101
	v_cvt_pk_bf16_f32 v89, v102, v103
	v_cvt_pk_bf16_f32 v90, v96, v97
	v_cvt_pk_bf16_f32 v91, v98, v99
	global_store_dwordx4 v[92:93], v[76:79], off offset:256
	v_cvt_pk_bf16_f32 v74, v80, v81
	v_cvt_pk_bf16_f32 v75, v82, v83
	v_lshl_add_u64 v[76:77], v[72:73], 0, v[142:143]
	v_cvt_pk_bf16_f32 v72, v84, v85
	v_cvt_pk_bf16_f32 v73, v86, v87
	v_cvt_pk_bf16_f32 v71, v66, v67
	v_cvt_pk_bf16_f32 v60, v60, v61
	v_cvt_pk_bf16_f32 v61, v62, v63
	v_cvt_pk_bf16_f32 v62, v56, v57
	v_cvt_pk_bf16_f32 v63, v58, v59
	v_cvt_pk_bf16_f32 v40, v52, v53
	v_cvt_pk_bf16_f32 v41, v54, v55
	v_cvt_pk_bf16_f32 v42, v48, v49
	v_cvt_pk_bf16_f32 v43, v50, v51
	v_cvt_pk_bf16_f32 v24, v36, v37
	v_cvt_pk_bf16_f32 v25, v38, v39
	v_cvt_pk_bf16_f32 v26, v32, v33
	v_cvt_pk_bf16_f32 v27, v34, v35
	global_store_dwordx4 v[28:29], v[12:15], off offset:256
	v_cvt_pk_bf16_f32 v10, v16, v17
	v_cvt_pk_bf16_f32 v11, v18, v19
	v_lshl_add_u64 v[12:13], v[8:9], 0, v[142:143]
	v_cvt_pk_bf16_f32 v8, v20, v21
	v_cvt_pk_bf16_f32 v9, v22, v23
	v_cvt_pk_bf16_f32 v4, v4, v5
	v_cvt_pk_bf16_f32 v5, v6, v7
	v_cvt_pk_bf16_f32 v6, v0, v1
	v_cvt_pk_bf16_f32 v7, v2, v3
	s_and_b64 vcc, exec, s[38:39]
	s_mov_b32 s34, s4
	s_mov_b32 s0, s6
	s_mov_b64 s[14:15], s[10:11]
	s_mov_b64 s[12:13], s[8:9]
	global_store_dwordx4 v[146:147], v[124:127], off
	global_store_dwordx4 v[108:109], v[104:107], off
	global_store_dwordx4 v[92:93], v[88:91], off
	global_store_dwordx4 v[76:77], v[72:75], off
	global_store_dwordx4 v[76:77], v[68:71], off offset:256
	global_store_dwordx4 v[64:65], v[60:63], off
	global_store_dwordx4 v[44:45], v[40:43], off
	global_store_dwordx4 v[28:29], v[24:27], off
	global_store_dwordx4 v[12:13], v[8:11], off
	global_store_dwordx4 v[12:13], v[4:7], off offset:256
	s_cbranch_vccz .LBB0_355
	s_waitcnt vmcnt(0)
	v_readlane_b32 s22, v255, 14
	s_cmpk_gt_u32 s19, 0xff
	v_readlane_b32 s23, v255, 15
	s_mov_b64 s[28:29], s[54:55]
	s_cbranch_scc1 .LBB0_362
	s_barrier
